# attention: softmax reference folded into QK MFMA (bf16-exact shift with 4-unit headroom), packed row sums; scan: y-reduction tail software-pipelined into next group
# speedup vs baseline: 1.0353x; 1.0353x over previous
; template <int CTRL> DI float dppf(float v) { return __int_as_float(__builtin_amdgcn_update_dpp(0, __float_as_int(v), CTRL, 0xf, 0xf, false)); }
; DI float red16(float p) { p += dppf<0xB1>(p); p += dppf<0x4E>(p); p += dppf<0x141>(p); p += dppf<0x140>(p); return p; }
; DI void scan_task(const Params& P, int sb, unsigned char* lds) {
;     ...
;         const float4 v4 = *(const float4*)(vrow + g4 * 4);
;         float pp[4];
; #pragma unroll
;         for (int i = 0; i < 4; ++i) {
;           ld_ops(nx3, gb + (i + 3) * SREC, q4);
;           const f2 a01 = {cur.a.x, cur.a.y}, a23 = {cur.a.z, cur.a.w}, w01 = {cur.w.x, cur.w.y}, w23 = {cur.w.z, cur.w.w};
;           const f2 k01 = {cur.k.x, cur.k.y}, k23 = {cur.k.z, cur.k.w}, b01 = {cur.b.x, cur.b.y}, b23 = {cur.b.z, cur.b.w};
;           const f2 r01 = {cur.r.x, cur.r.y}, r23 = {cur.r.z, cur.r.w};
;           f2 pa = S0 * a01; pa += S1 * a23;
;           const float vs = (i == 0) ? v4.x : (i == 1) ? v4.y : (i == 2) ? v4.z : v4.w;
;           const f2 vv = {vs, vs};
;           const f2 t0 = S0 * w01 + vv * k01, t1 = S1 * w23 + vv * k23;
;           const float sa = red16(pa.x + pa.y);
;           const f2 sa2 = {sa, sa};
;           S0 = t0 + sa2 * b01; S1 = t1 + sa2 * b23;
;           f2 py = S0 * r01; py += S1 * r23;
;           pp[i] = py.x + py.y;
;           cur = nxt; nxt = nx2; nx2 = nx3;
;         }
;         const float tA = o1 ? pp[0] : pp[1], kA = o1 ? pp[1] : pp[0];
;         const float tB = o1 ? pp[2] : pp[3], kB = o1 ? pp[3] : pp[2];
;         const float r0 = kA + dppf<0xB1>(tA), r1 = kB + dppf<0xB1>(tB);
;         const float tC = o2 ? r0 : r1, kC = o2 ? r1 : r0;
;         float u = kC + dppf<0x4E>(tC);
;         u += dppf<0x124>(u);
;         u += dppf<0x128>(u);
;         yb[(g4 * 4 + (q & 3)) * 16 + rowl] = u;
.LBB0_1198:
	v_add_u32_e32 v100, 0x18000, v74
	s_waitcnt lgkmcnt(14)
	v_pk_mul_f32 v[2:3], v[64:65], v[2:3]
	ds_read_b128 v[60:63], v72 offset:256
	ds_read_b128 v[76:79], v72 offset:512
	ds_read_b128 v[80:83], v72 offset:768
	ds_read_b128 v[84:87], v72 offset:1024
	ds_read_b128 v[88:91], v100
	ds_read_b128 v[92:95], v72
	v_pk_fma_f32 v[96:97], v[66:67], v[0:1], v[2:3]
	ds_read_b128 v[0:3], v72 offset:1408
	v_add_f32_e32 v75, v96, v97
	s_waitcnt lgkmcnt(2)
	v_pk_mul_f32 v[14:15], v[14:15], v[88:89] op_sel_hi:[1,0]
	v_pk_mul_f32 v[12:13], v[12:13], v[88:89] op_sel_hi:[1,0]
	v_add_f32_dpp v75, v75, v75 quad_perm:[1,0,3,2] row_mask:0xf bank_mask:0xf bound_ctrl:1
	v_pk_fma_f32 v[64:65], v[64:65], v[10:11], v[14:15]
	v_pk_fma_f32 v[66:67], v[66:67], v[8:9], v[12:13]
	v_add_f32_dpp v75, v75, v75 quad_perm:[2,3,0,1] row_mask:0xf bank_mask:0xf bound_ctrl:1
	v_mov_b32_e32 v98, v91
	ds_read_b128 v[8:11], v72 offset:1920
	ds_read_b128 v[12:15], v72 offset:2176
	v_add_f32_dpp v75, v75, v75 row_half_mirror row_mask:0xf bank_mask:0xf bound_ctrl:1
	s_nop 1
	v_add_f32_dpp v96, v75, v75 row_mirror row_mask:0xf bank_mask:0xf bound_ctrl:1
	v_pk_fma_f32 v[64:65], v[6:7], v[96:97], v[64:65] op_sel_hi:[1,0,1]
	v_pk_fma_f32 v[66:67], v[4:5], v[96:97], v[66:67] op_sel_hi:[1,0,1]
	v_pk_mul_f32 v[18:19], v[18:19], v[64:65]
	v_pk_mul_f32 v[22:23], v[22:23], v[64:65]
	v_pk_mul_f32 v[36:37], v[36:37], v[66:67]
	v_pk_mul_f32 v[38:39], v[38:39], v[64:65]
	v_pk_fma_f32 v[64:65], v[16:17], v[66:67], v[18:19]
	v_pk_fma_f32 v[66:67], v[20:21], v[66:67], v[22:23]
	v_add_f32_e32 v75, v64, v65
	v_add_f32_e32 v64, v66, v67
	v_pk_fma_f32 v[36:37], v[28:29], v[88:89], v[36:37] op_sel:[0,1,0]
	v_pk_fma_f32 v[38:39], v[30:31], v[88:89], v[38:39] op_sel:[0,1,0]
	v_add_f32_dpp v64, v64, v64 quad_perm:[1,0,3,2] row_mask:0xf bank_mask:0xf bound_ctrl:1
	ds_read_b128 v[4:7], v72 offset:1664
	ds_read_b128 v[16:19], v72 offset:2432
	ds_read_b128 v[20:23], v72 offset:2816
	ds_read_b128 v[28:31], v72 offset:3584
	v_add_f32_dpp v64, v64, v64 quad_perm:[2,3,0,1] row_mask:0xf bank_mask:0xf bound_ctrl:1
	s_nop 1
	v_add_f32_dpp v64, v64, v64 row_half_mirror row_mask:0xf bank_mask:0xf bound_ctrl:1
	s_nop 1
	v_add_f32_dpp v64, v64, v64 row_mirror row_mask:0xf bank_mask:0xf bound_ctrl:1
	v_pk_fma_f32 v[66:67], v[24:25], v[64:65], v[36:37] op_sel_hi:[1,0,1]
	v_pk_fma_f32 v[64:65], v[26:27], v[64:65], v[38:39] op_sel_hi:[1,0,1]
	v_pk_mul_f32 v[88:89], v[48:49], v[66:67]
	v_pk_mul_f32 v[34:35], v[34:35], v[64:65]
	v_pk_mul_f32 v[42:43], v[42:43], v[64:65]
	v_pk_fma_f32 v[96:97], v[32:33], v[66:67], v[34:35]
	v_pk_fma_f32 v[66:67], v[40:41], v[66:67], v[42:43]
	v_pk_mul_f32 v[64:65], v[50:51], v[64:65]
	v_add_f32_e32 v66, v66, v67
	v_pk_fma_f32 v[88:89], v[52:53], v[90:91], v[88:89] op_sel_hi:[1,0,1]
	v_pk_fma_f32 v[64:65], v[54:55], v[90:91], v[64:65] op_sel_hi:[1,0,1]
	v_add_f32_dpp v66, v66, v66 quad_perm:[1,0,3,2] row_mask:0xf bank_mask:0xf bound_ctrl:1
	v_add_f32_e32 v90, v96, v97
	v_cndmask_b32_e32 v67, v75, v90, vcc
	v_add_f32_dpp v66, v66, v66 quad_perm:[2,3,0,1] row_mask:0xf bank_mask:0xf bound_ctrl:1
	v_cndmask_b32_e32 v75, v90, v75, vcc
	ds_read_b128 v[24:27], v72 offset:3072
	ds_read_b128 v[36:39], v72 offset:3328
	v_add_f32_dpp v66, v66, v66 row_half_mirror row_mask:0xf bank_mask:0xf bound_ctrl:1
	v_add_f32_dpp v105, v67, v75 quad_perm:[1,0,3,2] row_mask:0xf bank_mask:0xf bound_ctrl:1
	ds_read_b128 v[48:51], v72 offset:4736
	ds_read_b128 v[32:35], v72 offset:3840
	v_add_f32_dpp v66, v66, v66 row_mirror row_mask:0xf bank_mask:0xf bound_ctrl:1
	v_pk_fma_f32 v[64:65], v[46:47], v[66:67], v[64:65] op_sel_hi:[1,0,1]
	v_pk_fma_f32 v[88:89], v[44:45], v[66:67], v[88:89] op_sel_hi:[1,0,1]
	s_waitcnt lgkmcnt(11)
	v_pk_mul_f32 v[66:67], v[94:95], v[64:65]
	v_pk_mul_f32 v[58:59], v[58:59], v[64:65]
	v_pk_fma_f32 v[66:67], v[92:93], v[88:89], v[66:67]
	v_pk_mul_f32 v[64:65], v[78:79], v[64:65]
	v_add_f32_e32 v66, v66, v67
	v_pk_fma_f32 v[78:79], v[56:57], v[88:89], v[58:59]
	v_pk_mul_f32 v[76:77], v[76:77], v[88:89]
	v_add_f32_dpp v66, v66, v66 quad_perm:[1,0,3,2] row_mask:0xf bank_mask:0xf bound_ctrl:1
	v_pk_fma_f32 v[64:65], v[98:99], v[82:83], v[64:65] op_sel_hi:[0,1,1]
	v_add_f32_e32 v104, v78, v79
	v_add_f32_dpp v66, v66, v66 quad_perm:[2,3,0,1] row_mask:0xf bank_mask:0xf bound_ctrl:1
	v_pk_fma_f32 v[76:77], v[98:99], v[80:81], v[76:77] op_sel_hi:[0,1,1]
	ds_read_b128 v[40:43], v72 offset:4224
	ds_read_b128 v[52:55], v72 offset:4992
	v_add_f32_dpp v66, v66, v66 row_half_mirror row_mask:0xf bank_mask:0xf bound_ctrl:1
	ds_read_b128 v[44:47], v72 offset:4480
	ds_read_b128 v[56:59], v72 offset:5248
	v_add_f32_dpp v78, v66, v66 row_mirror row_mask:0xf bank_mask:0xf bound_ctrl:1
	v_pk_fma_f32 v[64:65], v[62:63], v[78:79], v[64:65] op_sel_hi:[1,0,1]
	v_pk_fma_f32 v[66:67], v[60:61], v[78:79], v[76:77] op_sel_hi:[1,0,1]
	v_pk_mul_f32 v[102:103], v[86:87], v[64:65]
	v_pk_fma_f32 v[102:103], v[84:85], v[66:67], v[102:103]
	s_waitcnt lgkmcnt(14)
	v_pk_mul_f32 v[2:3], v[64:65], v[2:3]
	v_add_f32_e32 v102, v102, v103
	ds_read_b128 v[60:63], v72 offset:5888
	v_cndmask_b32_e32 v106, v104, v102, vcc
	v_cndmask_b32_e32 v102, v102, v104, vcc
	ds_read_b128 v[76:79], v72 offset:6144
	ds_read_b128 v[80:83], v72 offset:6400
	ds_read_b128 v[84:87], v72 offset:6656
	ds_read_b128 v[88:91], v100 offset:16
	ds_read_b128 v[92:95], v72 offset:5632
	v_add_f32_dpp v102, v106, v102 quad_perm:[1,0,3,2] row_mask:0xf bank_mask:0xf bound_ctrl:1
	v_pk_fma_f32 v[96:97], v[66:67], v[0:1], v[2:3]
	v_cndmask_b32_e64 v106, v105, v102, s[4:5]
	v_cndmask_b32_e64 v102, v102, v105, s[4:5]
	ds_read_b128 v[0:3], v72 offset:7040
	v_add_f32_e32 v75, v96, v97
	s_waitcnt lgkmcnt(2)
; template <int CTRL> DI float dppf(float v) { return __int_as_float(__builtin_amdgcn_update_dpp(0, __float_as_int(v), CTRL, 0xf, 0xf, false)); }
; DI float red16(float p) { p += dppf<0xB1>(p); p += dppf<0x4E>(p); p += dppf<0x141>(p); p += dppf<0x140>(p); return p; }
; DI void scan_task(const Params& P, int sb, unsigned char* lds) {
;     ...
;         const float4 v4 = *(const float4*)(vrow + g4 * 4);
;         float pp[4];
; #pragma unroll
;         for (int i = 0; i < 4; ++i) {
;           ld_ops(nx3, gb + (i + 3) * SREC, q4);
;           const f2 a01 = {cur.a.x, cur.a.y}, a23 = {cur.a.z, cur.a.w}, w01 = {cur.w.x, cur.w.y}, w23 = {cur.w.z, cur.w.w};
;           const f2 k01 = {cur.k.x, cur.k.y}, k23 = {cur.k.z, cur.k.w}, b01 = {cur.b.x, cur.b.y}, b23 = {cur.b.z, cur.b.w};
;           const f2 r01 = {cur.r.x, cur.r.y}, r23 = {cur.r.z, cur.r.w};
;           f2 pa = S0 * a01; pa += S1 * a23;
;           const float vs = (i == 0) ? v4.x : (i == 1) ? v4.y : (i == 2) ? v4.z : v4.w;
;           const f2 vv = {vs, vs};
;           const f2 t0 = S0 * w01 + vv * k01, t1 = S1 * w23 + vv * k23;
;           const float sa = red16(pa.x + pa.y);
;           const f2 sa2 = {sa, sa};
;           S0 = t0 + sa2 * b01; S1 = t1 + sa2 * b23;
;           f2 py = S0 * r01; py += S1 * r23;
;           pp[i] = py.x + py.y;
;           cur = nxt; nxt = nx2; nx2 = nx3;
;         }
;         const float tA = o1 ? pp[0] : pp[1], kA = o1 ? pp[1] : pp[0];
;         const float tB = o1 ? pp[2] : pp[3], kB = o1 ? pp[3] : pp[2];
;         const float r0 = kA + dppf<0xB1>(tA), r1 = kB + dppf<0xB1>(tB);
;         const float tC = o2 ? r0 : r1, kC = o2 ? r1 : r0;
;         float u = kC + dppf<0x4E>(tC);
;         u += dppf<0x124>(u);
;         u += dppf<0x128>(u);
;         yb[(g4 * 4 + (q & 3)) * 16 + rowl] = u;
	v_add_f32_dpp v102, v106, v102 quad_perm:[2,3,0,1] row_mask:0xf bank_mask:0xf bound_ctrl:1
	v_pk_mul_f32 v[14:15], v[14:15], v[88:89] op_sel_hi:[1,0]
	v_pk_mul_f32 v[12:13], v[12:13], v[88:89] op_sel_hi:[1,0]
	v_add_f32_dpp v102, v102, v102 row_ror:4 row_mask:0xf bank_mask:0xf bound_ctrl:1
	v_add_f32_dpp v75, v75, v75 quad_perm:[1,0,3,2] row_mask:0xf bank_mask:0xf bound_ctrl:1
	v_pk_fma_f32 v[64:65], v[64:65], v[10:11], v[14:15]
	v_pk_fma_f32 v[66:67], v[66:67], v[8:9], v[12:13]
	v_add_f32_dpp v102, v102, v102 row_ror:8 row_mask:0xf bank_mask:0xf bound_ctrl:1
	v_add_f32_dpp v75, v75, v75 quad_perm:[2,3,0,1] row_mask:0xf bank_mask:0xf bound_ctrl:1
	v_mov_b32_e32 v98, v91
	ds_write_b32 v73, v102
	ds_read_b128 v[8:11], v72 offset:7552
	ds_read_b128 v[12:15], v72 offset:7808
	v_add_f32_dpp v75, v75, v75 row_half_mirror row_mask:0xf bank_mask:0xf bound_ctrl:1
	s_nop 1
	v_add_f32_dpp v96, v75, v75 row_mirror row_mask:0xf bank_mask:0xf bound_ctrl:1
	v_pk_fma_f32 v[64:65], v[6:7], v[96:97], v[64:65] op_sel_hi:[1,0,1]
	v_pk_fma_f32 v[66:67], v[4:5], v[96:97], v[66:67] op_sel_hi:[1,0,1]
	v_pk_mul_f32 v[18:19], v[18:19], v[64:65]
	v_pk_mul_f32 v[22:23], v[22:23], v[64:65]
	v_pk_mul_f32 v[36:37], v[36:37], v[66:67]
	v_pk_mul_f32 v[38:39], v[38:39], v[64:65]
	v_pk_fma_f32 v[64:65], v[16:17], v[66:67], v[18:19]
	v_pk_fma_f32 v[66:67], v[20:21], v[66:67], v[22:23]
	v_add_f32_e32 v75, v64, v65
	v_add_f32_e32 v64, v66, v67
	v_pk_fma_f32 v[36:37], v[28:29], v[88:89], v[36:37] op_sel:[0,1,0]
	v_pk_fma_f32 v[38:39], v[30:31], v[88:89], v[38:39] op_sel:[0,1,0]
	v_add_f32_dpp v64, v64, v64 quad_perm:[1,0,3,2] row_mask:0xf bank_mask:0xf bound_ctrl:1
	ds_read_b128 v[4:7], v72 offset:7296
	ds_read_b128 v[16:19], v72 offset:8064
	ds_read_b128 v[20:23], v72 offset:8448
	ds_read_b128 v[28:31], v72 offset:9216
	v_add_f32_dpp v64, v64, v64 quad_perm:[2,3,0,1] row_mask:0xf bank_mask:0xf bound_ctrl:1
	s_nop 1
	v_add_f32_dpp v64, v64, v64 row_half_mirror row_mask:0xf bank_mask:0xf bound_ctrl:1
	s_nop 1
	v_add_f32_dpp v64, v64, v64 row_mirror row_mask:0xf bank_mask:0xf bound_ctrl:1
	v_pk_fma_f32 v[66:67], v[24:25], v[64:65], v[36:37] op_sel_hi:[1,0,1]
	v_pk_fma_f32 v[64:65], v[26:27], v[64:65], v[38:39] op_sel_hi:[1,0,1]
	v_pk_mul_f32 v[88:89], v[48:49], v[66:67]
	v_pk_mul_f32 v[34:35], v[34:35], v[64:65]
	v_pk_mul_f32 v[42:43], v[42:43], v[64:65]
	v_pk_fma_f32 v[96:97], v[32:33], v[66:67], v[34:35]
	v_pk_fma_f32 v[66:67], v[40:41], v[66:67], v[42:43]
	v_pk_mul_f32 v[64:65], v[50:51], v[64:65]
	v_add_f32_e32 v66, v66, v67
	v_pk_fma_f32 v[88:89], v[52:53], v[90:91], v[88:89] op_sel_hi:[1,0,1]
	v_pk_fma_f32 v[64:65], v[54:55], v[90:91], v[64:65] op_sel_hi:[1,0,1]
	v_add_f32_dpp v66, v66, v66 quad_perm:[1,0,3,2] row_mask:0xf bank_mask:0xf bound_ctrl:1
	v_add_f32_e32 v90, v96, v97
	v_cndmask_b32_e32 v67, v75, v90, vcc
	v_add_f32_dpp v66, v66, v66 quad_perm:[2,3,0,1] row_mask:0xf bank_mask:0xf bound_ctrl:1
	v_cndmask_b32_e32 v75, v90, v75, vcc
	ds_read_b128 v[24:27], v72 offset:8704
	ds_read_b128 v[36:39], v72 offset:8960
	v_add_f32_dpp v66, v66, v66 row_half_mirror row_mask:0xf bank_mask:0xf bound_ctrl:1
	v_add_f32_dpp v105, v67, v75 quad_perm:[1,0,3,2] row_mask:0xf bank_mask:0xf bound_ctrl:1
	ds_read_b128 v[48:51], v72 offset:10368
	ds_read_b128 v[32:35], v72 offset:9472
	v_add_f32_dpp v66, v66, v66 row_mirror row_mask:0xf bank_mask:0xf bound_ctrl:1
	v_pk_fma_f32 v[64:65], v[46:47], v[66:67], v[64:65] op_sel_hi:[1,0,1]
	v_pk_fma_f32 v[88:89], v[44:45], v[66:67], v[88:89] op_sel_hi:[1,0,1]
	s_waitcnt lgkmcnt(11)
	v_pk_mul_f32 v[66:67], v[94:95], v[64:65]
	v_pk_mul_f32 v[58:59], v[58:59], v[64:65]
	v_pk_fma_f32 v[66:67], v[92:93], v[88:89], v[66:67]
	v_pk_mul_f32 v[64:65], v[78:79], v[64:65]
	v_add_f32_e32 v66, v66, v67
	v_pk_fma_f32 v[78:79], v[56:57], v[88:89], v[58:59]
	v_pk_mul_f32 v[76:77], v[76:77], v[88:89]
	v_add_f32_dpp v66, v66, v66 quad_perm:[1,0,3,2] row_mask:0xf bank_mask:0xf bound_ctrl:1
	v_pk_fma_f32 v[64:65], v[98:99], v[82:83], v[64:65] op_sel_hi:[0,1,1]
	v_add_f32_e32 v104, v78, v79
	v_add_f32_dpp v66, v66, v66 quad_perm:[2,3,0,1] row_mask:0xf bank_mask:0xf bound_ctrl:1
	v_pk_fma_f32 v[76:77], v[98:99], v[80:81], v[76:77] op_sel_hi:[0,1,1]
	ds_read_b128 v[40:43], v72 offset:9856
	ds_read_b128 v[52:55], v72 offset:10624
	v_add_f32_dpp v66, v66, v66 row_half_mirror row_mask:0xf bank_mask:0xf bound_ctrl:1
	ds_read_b128 v[44:47], v72 offset:10112
	ds_read_b128 v[56:59], v72 offset:10880
	v_add_f32_dpp v78, v66, v66 row_mirror row_mask:0xf bank_mask:0xf bound_ctrl:1
	v_pk_fma_f32 v[64:65], v[62:63], v[78:79], v[64:65] op_sel_hi:[1,0,1]
	v_pk_fma_f32 v[66:67], v[60:61], v[78:79], v[76:77] op_sel_hi:[1,0,1]
	v_pk_mul_f32 v[102:103], v[86:87], v[64:65]
	v_pk_fma_f32 v[102:103], v[84:85], v[66:67], v[102:103]
	s_waitcnt lgkmcnt(14)
	v_pk_mul_f32 v[2:3], v[64:65], v[2:3]
	v_add_f32_e32 v102, v102, v103
	ds_read_b128 v[60:63], v72 offset:11520
	v_cndmask_b32_e32 v106, v104, v102, vcc
	v_cndmask_b32_e32 v102, v102, v104, vcc
	ds_read_b128 v[76:79], v72 offset:11776
	ds_read_b128 v[80:83], v72 offset:12032
	ds_read_b128 v[84:87], v72 offset:12288
	ds_read_b128 v[88:91], v100 offset:32
	ds_read_b128 v[92:95], v72 offset:11264
	v_add_f32_dpp v102, v106, v102 quad_perm:[1,0,3,2] row_mask:0xf bank_mask:0xf bound_ctrl:1
	v_pk_fma_f32 v[96:97], v[66:67], v[0:1], v[2:3]
	v_cndmask_b32_e64 v106, v105, v102, s[4:5]
	v_cndmask_b32_e64 v102, v102, v105, s[4:5]
	ds_read_b128 v[0:3], v72 offset:12672
	v_add_f32_e32 v75, v96, v97
	s_waitcnt lgkmcnt(2)
; template <int CTRL> DI float dppf(float v) { return __int_as_float(__builtin_amdgcn_update_dpp(0, __float_as_int(v), CTRL, 0xf, 0xf, false)); }
; DI float red16(float p) { p += dppf<0xB1>(p); p += dppf<0x4E>(p); p += dppf<0x141>(p); p += dppf<0x140>(p); return p; }
; DI void scan_task(const Params& P, int sb, unsigned char* lds) {
;     ...
;         const float4 v4 = *(const float4*)(vrow + g4 * 4);
;         float pp[4];
; #pragma unroll
;         for (int i = 0; i < 4; ++i) {
;           ld_ops(nx3, gb + (i + 3) * SREC, q4);
;           const f2 a01 = {cur.a.x, cur.a.y}, a23 = {cur.a.z, cur.a.w}, w01 = {cur.w.x, cur.w.y}, w23 = {cur.w.z, cur.w.w};
;           const f2 k01 = {cur.k.x, cur.k.y}, k23 = {cur.k.z, cur.k.w}, b01 = {cur.b.x, cur.b.y}, b23 = {cur.b.z, cur.b.w};
;           const f2 r01 = {cur.r.x, cur.r.y}, r23 = {cur.r.z, cur.r.w};
;           f2 pa = S0 * a01; pa += S1 * a23;
;           const float vs = (i == 0) ? v4.x : (i == 1) ? v4.y : (i == 2) ? v4.z : v4.w;
;           const f2 vv = {vs, vs};
;           const f2 t0 = S0 * w01 + vv * k01, t1 = S1 * w23 + vv * k23;
;           const float sa = red16(pa.x + pa.y);
;           const f2 sa2 = {sa, sa};
;           S0 = t0 + sa2 * b01; S1 = t1 + sa2 * b23;
;           f2 py = S0 * r01; py += S1 * r23;
;           pp[i] = py.x + py.y;
;           cur = nxt; nxt = nx2; nx2 = nx3;
;         }
;         const float tA = o1 ? pp[0] : pp[1], kA = o1 ? pp[1] : pp[0];
;         const float tB = o1 ? pp[2] : pp[3], kB = o1 ? pp[3] : pp[2];
;         const float r0 = kA + dppf<0xB1>(tA), r1 = kB + dppf<0xB1>(tB);
;         const float tC = o2 ? r0 : r1, kC = o2 ? r1 : r0;
;         float u = kC + dppf<0x4E>(tC);
;         u += dppf<0x124>(u);
;         u += dppf<0x128>(u);
;         yb[(g4 * 4 + (q & 3)) * 16 + rowl] = u;
	v_add_f32_dpp v102, v106, v102 quad_perm:[2,3,0,1] row_mask:0xf bank_mask:0xf bound_ctrl:1
	v_pk_mul_f32 v[14:15], v[14:15], v[88:89] op_sel_hi:[1,0]
	v_pk_mul_f32 v[12:13], v[12:13], v[88:89] op_sel_hi:[1,0]
	v_add_f32_dpp v102, v102, v102 row_ror:4 row_mask:0xf bank_mask:0xf bound_ctrl:1
	v_add_f32_dpp v75, v75, v75 quad_perm:[1,0,3,2] row_mask:0xf bank_mask:0xf bound_ctrl:1
	v_pk_fma_f32 v[64:65], v[64:65], v[10:11], v[14:15]
	v_pk_fma_f32 v[66:67], v[66:67], v[8:9], v[12:13]
	v_add_f32_dpp v102, v102, v102 row_ror:8 row_mask:0xf bank_mask:0xf bound_ctrl:1
	v_add_f32_dpp v75, v75, v75 quad_perm:[2,3,0,1] row_mask:0xf bank_mask:0xf bound_ctrl:1
	v_mov_b32_e32 v98, v91
	ds_write_b32 v73, v102 offset:256
	ds_read_b128 v[8:11], v72 offset:13184
	ds_read_b128 v[12:15], v72 offset:13440
	v_add_f32_dpp v75, v75, v75 row_half_mirror row_mask:0xf bank_mask:0xf bound_ctrl:1
	s_nop 1
	v_add_f32_dpp v96, v75, v75 row_mirror row_mask:0xf bank_mask:0xf bound_ctrl:1
	v_pk_fma_f32 v[64:65], v[6:7], v[96:97], v[64:65] op_sel_hi:[1,0,1]
	v_pk_fma_f32 v[66:67], v[4:5], v[96:97], v[66:67] op_sel_hi:[1,0,1]
	v_pk_mul_f32 v[18:19], v[18:19], v[64:65]
	v_pk_mul_f32 v[22:23], v[22:23], v[64:65]
	v_pk_mul_f32 v[36:37], v[36:37], v[66:67]
	v_pk_mul_f32 v[38:39], v[38:39], v[64:65]
	v_pk_fma_f32 v[64:65], v[16:17], v[66:67], v[18:19]
	v_pk_fma_f32 v[66:67], v[20:21], v[66:67], v[22:23]
	v_add_f32_e32 v75, v64, v65
	v_add_f32_e32 v64, v66, v67
	v_pk_fma_f32 v[36:37], v[28:29], v[88:89], v[36:37] op_sel:[0,1,0]
	v_pk_fma_f32 v[38:39], v[30:31], v[88:89], v[38:39] op_sel:[0,1,0]
	v_add_f32_dpp v64, v64, v64 quad_perm:[1,0,3,2] row_mask:0xf bank_mask:0xf bound_ctrl:1
	ds_read_b128 v[4:7], v72 offset:12928
	ds_read_b128 v[16:19], v72 offset:13696
	ds_read_b128 v[20:23], v72 offset:14080
	ds_read_b128 v[28:31], v72 offset:14848
	v_add_f32_dpp v64, v64, v64 quad_perm:[2,3,0,1] row_mask:0xf bank_mask:0xf bound_ctrl:1
	s_nop 1
	v_add_f32_dpp v64, v64, v64 row_half_mirror row_mask:0xf bank_mask:0xf bound_ctrl:1
	s_nop 1
	v_add_f32_dpp v64, v64, v64 row_mirror row_mask:0xf bank_mask:0xf bound_ctrl:1
	v_pk_fma_f32 v[66:67], v[24:25], v[64:65], v[36:37] op_sel_hi:[1,0,1]
	v_pk_fma_f32 v[64:65], v[26:27], v[64:65], v[38:39] op_sel_hi:[1,0,1]
	v_pk_mul_f32 v[88:89], v[48:49], v[66:67]
	v_pk_mul_f32 v[34:35], v[34:35], v[64:65]
	v_pk_mul_f32 v[42:43], v[42:43], v[64:65]
	v_pk_fma_f32 v[96:97], v[32:33], v[66:67], v[34:35]
	v_pk_fma_f32 v[66:67], v[40:41], v[66:67], v[42:43]
	v_pk_mul_f32 v[64:65], v[50:51], v[64:65]
	v_add_f32_e32 v66, v66, v67
	v_pk_fma_f32 v[88:89], v[52:53], v[90:91], v[88:89] op_sel_hi:[1,0,1]
	v_pk_fma_f32 v[64:65], v[54:55], v[90:91], v[64:65] op_sel_hi:[1,0,1]
	v_add_f32_dpp v66, v66, v66 quad_perm:[1,0,3,2] row_mask:0xf bank_mask:0xf bound_ctrl:1
	v_add_f32_e32 v90, v96, v97
	v_cndmask_b32_e32 v67, v75, v90, vcc
	v_add_f32_dpp v66, v66, v66 quad_perm:[2,3,0,1] row_mask:0xf bank_mask:0xf bound_ctrl:1
	v_cndmask_b32_e32 v75, v90, v75, vcc
	ds_read_b128 v[24:27], v72 offset:14336
	ds_read_b128 v[36:39], v72 offset:14592
	v_add_f32_dpp v66, v66, v66 row_half_mirror row_mask:0xf bank_mask:0xf bound_ctrl:1
	v_add_f32_dpp v105, v67, v75 quad_perm:[1,0,3,2] row_mask:0xf bank_mask:0xf bound_ctrl:1
	ds_read_b128 v[48:51], v72 offset:16000
	ds_read_b128 v[32:35], v72 offset:15104
	v_add_f32_dpp v66, v66, v66 row_mirror row_mask:0xf bank_mask:0xf bound_ctrl:1
	v_pk_fma_f32 v[64:65], v[46:47], v[66:67], v[64:65] op_sel_hi:[1,0,1]
	v_pk_fma_f32 v[88:89], v[44:45], v[66:67], v[88:89] op_sel_hi:[1,0,1]
	s_waitcnt lgkmcnt(11)
	v_pk_mul_f32 v[66:67], v[94:95], v[64:65]
	v_pk_mul_f32 v[58:59], v[58:59], v[64:65]
	v_pk_fma_f32 v[66:67], v[92:93], v[88:89], v[66:67]
	v_pk_mul_f32 v[64:65], v[78:79], v[64:65]
	v_add_f32_e32 v66, v66, v67
	v_pk_fma_f32 v[78:79], v[56:57], v[88:89], v[58:59]
	v_pk_mul_f32 v[76:77], v[76:77], v[88:89]
	v_add_f32_dpp v66, v66, v66 quad_perm:[1,0,3,2] row_mask:0xf bank_mask:0xf bound_ctrl:1
	v_pk_fma_f32 v[64:65], v[98:99], v[82:83], v[64:65] op_sel_hi:[0,1,1]
	v_add_f32_e32 v104, v78, v79
	v_add_f32_dpp v66, v66, v66 quad_perm:[2,3,0,1] row_mask:0xf bank_mask:0xf bound_ctrl:1
	v_pk_fma_f32 v[76:77], v[98:99], v[80:81], v[76:77] op_sel_hi:[0,1,1]
	ds_read_b128 v[40:43], v72 offset:15488
	ds_read_b128 v[52:55], v72 offset:16256
	v_add_f32_dpp v66, v66, v66 row_half_mirror row_mask:0xf bank_mask:0xf bound_ctrl:1
	ds_read_b128 v[44:47], v72 offset:15744
	ds_read_b128 v[56:59], v72 offset:16512
	v_add_f32_dpp v78, v66, v66 row_mirror row_mask:0xf bank_mask:0xf bound_ctrl:1
	v_pk_fma_f32 v[64:65], v[62:63], v[78:79], v[64:65] op_sel_hi:[1,0,1]
	v_pk_fma_f32 v[66:67], v[60:61], v[78:79], v[76:77] op_sel_hi:[1,0,1]
	v_pk_mul_f32 v[102:103], v[86:87], v[64:65]
	v_pk_fma_f32 v[102:103], v[84:85], v[66:67], v[102:103]
	s_waitcnt lgkmcnt(14)
	v_pk_mul_f32 v[2:3], v[64:65], v[2:3]
	v_add_f32_e32 v102, v102, v103
	ds_read_b128 v[60:63], v72 offset:17152
	v_cndmask_b32_e32 v106, v104, v102, vcc
	v_cndmask_b32_e32 v102, v102, v104, vcc
	ds_read_b128 v[76:79], v72 offset:17408
	ds_read_b128 v[80:83], v72 offset:17664
	ds_read_b128 v[84:87], v72 offset:17920
	ds_read_b128 v[88:91], v100 offset:48
	ds_read_b128 v[92:95], v72 offset:16896
	v_add_f32_dpp v102, v106, v102 quad_perm:[1,0,3,2] row_mask:0xf bank_mask:0xf bound_ctrl:1
	v_pk_fma_f32 v[96:97], v[66:67], v[0:1], v[2:3]
	v_cndmask_b32_e64 v106, v105, v102, s[4:5]
	v_cndmask_b32_e64 v102, v102, v105, s[4:5]
	ds_read_b128 v[0:3], v72 offset:18304
	v_add_f32_e32 v75, v96, v97
	s_waitcnt lgkmcnt(2)
; template <int CTRL> DI float dppf(float v) { return __int_as_float(__builtin_amdgcn_update_dpp(0, __float_as_int(v), CTRL, 0xf, 0xf, false)); }
; DI float red16(float p) { p += dppf<0xB1>(p); p += dppf<0x4E>(p); p += dppf<0x141>(p); p += dppf<0x140>(p); return p; }
; DI void scan_task(const Params& P, int sb, unsigned char* lds) {
;     ...
;         const float4 v4 = *(const float4*)(vrow + g4 * 4);
;         float pp[4];
; #pragma unroll
;         for (int i = 0; i < 4; ++i) {
;           ld_ops(nx3, gb + (i + 3) * SREC, q4);
;           const f2 a01 = {cur.a.x, cur.a.y}, a23 = {cur.a.z, cur.a.w}, w01 = {cur.w.x, cur.w.y}, w23 = {cur.w.z, cur.w.w};
;           const f2 k01 = {cur.k.x, cur.k.y}, k23 = {cur.k.z, cur.k.w}, b01 = {cur.b.x, cur.b.y}, b23 = {cur.b.z, cur.b.w};
;           const f2 r01 = {cur.r.x, cur.r.y}, r23 = {cur.r.z, cur.r.w};
;           f2 pa = S0 * a01; pa += S1 * a23;
;           const float vs = (i == 0) ? v4.x : (i == 1) ? v4.y : (i == 2) ? v4.z : v4.w;
;           const f2 vv = {vs, vs};
;           const f2 t0 = S0 * w01 + vv * k01, t1 = S1 * w23 + vv * k23;
;           const float sa = red16(pa.x + pa.y);
;           const f2 sa2 = {sa, sa};
;           S0 = t0 + sa2 * b01; S1 = t1 + sa2 * b23;
;           f2 py = S0 * r01; py += S1 * r23;
;           pp[i] = py.x + py.y;
;           cur = nxt; nxt = nx2; nx2 = nx3;
;         }
;         const float tA = o1 ? pp[0] : pp[1], kA = o1 ? pp[1] : pp[0];
;         const float tB = o1 ? pp[2] : pp[3], kB = o1 ? pp[3] : pp[2];
;         const float r0 = kA + dppf<0xB1>(tA), r1 = kB + dppf<0xB1>(tB);
;         const float tC = o2 ? r0 : r1, kC = o2 ? r1 : r0;
;         float u = kC + dppf<0x4E>(tC);
;         u += dppf<0x124>(u);
;         u += dppf<0x128>(u);
;         yb[(g4 * 4 + (q & 3)) * 16 + rowl] = u;
	v_add_f32_dpp v102, v106, v102 quad_perm:[2,3,0,1] row_mask:0xf bank_mask:0xf bound_ctrl:1
	v_pk_mul_f32 v[14:15], v[14:15], v[88:89] op_sel_hi:[1,0]
	v_pk_mul_f32 v[12:13], v[12:13], v[88:89] op_sel_hi:[1,0]
	v_add_f32_dpp v102, v102, v102 row_ror:4 row_mask:0xf bank_mask:0xf bound_ctrl:1
	v_add_f32_dpp v75, v75, v75 quad_perm:[1,0,3,2] row_mask:0xf bank_mask:0xf bound_ctrl:1
	v_pk_fma_f32 v[64:65], v[64:65], v[10:11], v[14:15]
	v_pk_fma_f32 v[66:67], v[66:67], v[8:9], v[12:13]
	v_add_f32_dpp v102, v102, v102 row_ror:8 row_mask:0xf bank_mask:0xf bound_ctrl:1
	v_add_f32_dpp v75, v75, v75 quad_perm:[2,3,0,1] row_mask:0xf bank_mask:0xf bound_ctrl:1
	v_mov_b32_e32 v98, v91
	ds_write_b32 v73, v102 offset:512
	ds_read_b128 v[8:11], v72 offset:18816
	ds_read_b128 v[12:15], v72 offset:19072
	v_add_f32_dpp v75, v75, v75 row_half_mirror row_mask:0xf bank_mask:0xf bound_ctrl:1
	s_nop 1
	v_add_f32_dpp v96, v75, v75 row_mirror row_mask:0xf bank_mask:0xf bound_ctrl:1
	v_pk_fma_f32 v[64:65], v[6:7], v[96:97], v[64:65] op_sel_hi:[1,0,1]
	v_pk_fma_f32 v[66:67], v[4:5], v[96:97], v[66:67] op_sel_hi:[1,0,1]
	v_pk_mul_f32 v[18:19], v[18:19], v[64:65]
	v_pk_mul_f32 v[22:23], v[22:23], v[64:65]
	v_pk_mul_f32 v[36:37], v[36:37], v[66:67]
	v_pk_mul_f32 v[38:39], v[38:39], v[64:65]
	v_pk_fma_f32 v[64:65], v[16:17], v[66:67], v[18:19]
	v_pk_fma_f32 v[66:67], v[20:21], v[66:67], v[22:23]
	v_add_f32_e32 v75, v64, v65
	v_add_f32_e32 v64, v66, v67
	v_pk_fma_f32 v[36:37], v[28:29], v[88:89], v[36:37] op_sel:[0,1,0]
	v_pk_fma_f32 v[38:39], v[30:31], v[88:89], v[38:39] op_sel:[0,1,0]
	v_add_f32_dpp v64, v64, v64 quad_perm:[1,0,3,2] row_mask:0xf bank_mask:0xf bound_ctrl:1
	ds_read_b128 v[4:7], v72 offset:18560
	ds_read_b128 v[16:19], v72 offset:19328
	ds_read_b128 v[20:23], v72 offset:19712
	ds_read_b128 v[28:31], v72 offset:20480
	v_add_f32_dpp v64, v64, v64 quad_perm:[2,3,0,1] row_mask:0xf bank_mask:0xf bound_ctrl:1
	s_nop 1
	v_add_f32_dpp v64, v64, v64 row_half_mirror row_mask:0xf bank_mask:0xf bound_ctrl:1
	s_nop 1
	v_add_f32_dpp v64, v64, v64 row_mirror row_mask:0xf bank_mask:0xf bound_ctrl:1
	v_pk_fma_f32 v[66:67], v[24:25], v[64:65], v[36:37] op_sel_hi:[1,0,1]
	v_pk_fma_f32 v[64:65], v[26:27], v[64:65], v[38:39] op_sel_hi:[1,0,1]
	v_pk_mul_f32 v[88:89], v[48:49], v[66:67]
	v_pk_mul_f32 v[34:35], v[34:35], v[64:65]
	v_pk_mul_f32 v[42:43], v[42:43], v[64:65]
	v_pk_fma_f32 v[96:97], v[32:33], v[66:67], v[34:35]
	v_pk_fma_f32 v[66:67], v[40:41], v[66:67], v[42:43]
	v_pk_mul_f32 v[64:65], v[50:51], v[64:65]
	v_add_f32_e32 v66, v66, v67
	v_pk_fma_f32 v[88:89], v[52:53], v[90:91], v[88:89] op_sel_hi:[1,0,1]
	v_pk_fma_f32 v[64:65], v[54:55], v[90:91], v[64:65] op_sel_hi:[1,0,1]
	v_add_f32_dpp v66, v66, v66 quad_perm:[1,0,3,2] row_mask:0xf bank_mask:0xf bound_ctrl:1
	v_add_f32_e32 v90, v96, v97
	v_cndmask_b32_e32 v67, v75, v90, vcc
	v_add_f32_dpp v66, v66, v66 quad_perm:[2,3,0,1] row_mask:0xf bank_mask:0xf bound_ctrl:1
	v_cndmask_b32_e32 v75, v90, v75, vcc
	ds_read_b128 v[24:27], v72 offset:19968
	ds_read_b128 v[36:39], v72 offset:20224
	v_add_f32_dpp v66, v66, v66 row_half_mirror row_mask:0xf bank_mask:0xf bound_ctrl:1
	v_add_f32_dpp v105, v67, v75 quad_perm:[1,0,3,2] row_mask:0xf bank_mask:0xf bound_ctrl:1
	ds_read_b128 v[48:51], v72 offset:21632
	ds_read_b128 v[32:35], v72 offset:20736
	v_add_f32_dpp v66, v66, v66 row_mirror row_mask:0xf bank_mask:0xf bound_ctrl:1
	v_pk_fma_f32 v[64:65], v[46:47], v[66:67], v[64:65] op_sel_hi:[1,0,1]
	v_pk_fma_f32 v[88:89], v[44:45], v[66:67], v[88:89] op_sel_hi:[1,0,1]
	s_waitcnt lgkmcnt(11)
	v_pk_mul_f32 v[66:67], v[94:95], v[64:65]
	v_pk_mul_f32 v[58:59], v[58:59], v[64:65]
	v_pk_fma_f32 v[66:67], v[92:93], v[88:89], v[66:67]
	v_pk_mul_f32 v[64:65], v[78:79], v[64:65]
	v_add_f32_e32 v66, v66, v67
	v_pk_fma_f32 v[78:79], v[56:57], v[88:89], v[58:59]
	v_pk_mul_f32 v[76:77], v[76:77], v[88:89]
	v_add_f32_dpp v66, v66, v66 quad_perm:[1,0,3,2] row_mask:0xf bank_mask:0xf bound_ctrl:1
	v_pk_fma_f32 v[64:65], v[98:99], v[82:83], v[64:65] op_sel_hi:[0,1,1]
	v_add_f32_e32 v104, v78, v79
	v_add_f32_dpp v66, v66, v66 quad_perm:[2,3,0,1] row_mask:0xf bank_mask:0xf bound_ctrl:1
	v_pk_fma_f32 v[76:77], v[98:99], v[80:81], v[76:77] op_sel_hi:[0,1,1]
	ds_read_b128 v[40:43], v72 offset:21120
	ds_read_b128 v[52:55], v72 offset:21888
	v_add_f32_dpp v66, v66, v66 row_half_mirror row_mask:0xf bank_mask:0xf bound_ctrl:1
	ds_read_b128 v[44:47], v72 offset:21376
	ds_read_b128 v[56:59], v72 offset:22144
	v_add_f32_dpp v78, v66, v66 row_mirror row_mask:0xf bank_mask:0xf bound_ctrl:1
	v_pk_fma_f32 v[64:65], v[62:63], v[78:79], v[64:65] op_sel_hi:[1,0,1]
	v_pk_fma_f32 v[66:67], v[60:61], v[78:79], v[76:77] op_sel_hi:[1,0,1]
	v_pk_mul_f32 v[102:103], v[86:87], v[64:65]
	v_pk_fma_f32 v[102:103], v[84:85], v[66:67], v[102:103]
	s_waitcnt lgkmcnt(14)
	v_pk_mul_f32 v[2:3], v[64:65], v[2:3]
	v_add_f32_e32 v102, v102, v103
	ds_read_b128 v[60:63], v72 offset:22784
	v_cndmask_b32_e32 v106, v104, v102, vcc
	v_cndmask_b32_e32 v102, v102, v104, vcc
	ds_read_b128 v[76:79], v72 offset:23040
	ds_read_b128 v[80:83], v72 offset:23296
	ds_read_b128 v[84:87], v72 offset:23552
	ds_read_b128 v[88:91], v100 offset:64
	ds_read_b128 v[92:95], v72 offset:22528
	v_add_f32_dpp v102, v106, v102 quad_perm:[1,0,3,2] row_mask:0xf bank_mask:0xf bound_ctrl:1
	v_pk_fma_f32 v[96:97], v[66:67], v[0:1], v[2:3]
	v_cndmask_b32_e64 v106, v105, v102, s[4:5]
	v_cndmask_b32_e64 v102, v102, v105, s[4:5]
	ds_read_b128 v[0:3], v72 offset:23936
	v_add_f32_e32 v75, v96, v97
	s_waitcnt lgkmcnt(2)
; template <int CTRL> DI float dppf(float v) { return __int_as_float(__builtin_amdgcn_update_dpp(0, __float_as_int(v), CTRL, 0xf, 0xf, false)); }
; DI float red16(float p) { p += dppf<0xB1>(p); p += dppf<0x4E>(p); p += dppf<0x141>(p); p += dppf<0x140>(p); return p; }
; DI void scan_task(const Params& P, int sb, unsigned char* lds) {
;     ...
;         for (int i = 0; i < 4; ++i) {
;           ld_ops(nx3, gb + (i + 3) * SREC, q4);
;           const f2 a01 = {cur.a.x, cur.a.y}, a23 = {cur.a.z, cur.a.w}, w01 = {cur.w.x, cur.w.y}, w23 = {cur.w.z, cur.w.w};
;           const f2 k01 = {cur.k.x, cur.k.y}, k23 = {cur.k.z, cur.k.w}, b01 = {cur.b.x, cur.b.y}, b23 = {cur.b.z, cur.b.w};
;           const f2 r01 = {cur.r.x, cur.r.y}, r23 = {cur.r.z, cur.r.w};
;           f2 pa = S0 * a01; pa += S1 * a23;
;           const float vs = (i == 0) ? v4.x : (i == 1) ? v4.y : (i == 2) ? v4.z : v4.w;
;           const f2 vv = {vs, vs};
;           const f2 t0 = S0 * w01 + vv * k01, t1 = S1 * w23 + vv * k23;
;           const float sa = red16(pa.x + pa.y);
;           const f2 sa2 = {sa, sa};
;           S0 = t0 + sa2 * b01; S1 = t1 + sa2 * b23;
;           f2 py = S0 * r01; py += S1 * r23;
;           pp[i] = py.x + py.y;
;           cur = nxt; nxt = nx2; nx2 = nx3;
;         }
;         const float tA = o1 ? pp[0] : pp[1], kA = o1 ? pp[1] : pp[0];
;         const float tB = o1 ? pp[2] : pp[3], kB = o1 ? pp[3] : pp[2];
;         const float r0 = kA + dppf<0xB1>(tA), r1 = kB + dppf<0xB1>(tB);
;         const float tC = o2 ? r0 : r1, kC = o2 ? r1 : r0;
;         float u = kC + dppf<0x4E>(tC);
;         u += dppf<0x124>(u);
;         u += dppf<0x128>(u);
;         yb[(g4 * 4 + (q & 3)) * 16 + rowl] = u;
	v_add_f32_dpp v102, v106, v102 quad_perm:[2,3,0,1] row_mask:0xf bank_mask:0xf bound_ctrl:1
	v_pk_mul_f32 v[14:15], v[14:15], v[88:89] op_sel_hi:[1,0]
	v_pk_mul_f32 v[12:13], v[12:13], v[88:89] op_sel_hi:[1,0]
	v_add_f32_dpp v102, v102, v102 row_ror:4 row_mask:0xf bank_mask:0xf bound_ctrl:1
	v_add_f32_dpp v75, v75, v75 quad_perm:[1,0,3,2] row_mask:0xf bank_mask:0xf bound_ctrl:1
	v_pk_fma_f32 v[64:65], v[64:65], v[10:11], v[14:15]
	v_pk_fma_f32 v[66:67], v[66:67], v[8:9], v[12:13]
	v_add_f32_dpp v102, v102, v102 row_ror:8 row_mask:0xf bank_mask:0xf bound_ctrl:1
	v_add_f32_dpp v75, v75, v75 quad_perm:[2,3,0,1] row_mask:0xf bank_mask:0xf bound_ctrl:1
	v_mov_b32_e32 v98, v91
	ds_write_b32 v73, v102 offset:768
	ds_read_b128 v[8:11], v72 offset:24448
	ds_read_b128 v[12:15], v72 offset:24704
	v_add_f32_dpp v75, v75, v75 row_half_mirror row_mask:0xf bank_mask:0xf bound_ctrl:1
	s_nop 1
	v_add_f32_dpp v96, v75, v75 row_mirror row_mask:0xf bank_mask:0xf bound_ctrl:1
	v_pk_fma_f32 v[64:65], v[6:7], v[96:97], v[64:65] op_sel_hi:[1,0,1]
	v_pk_fma_f32 v[66:67], v[4:5], v[96:97], v[66:67] op_sel_hi:[1,0,1]
	v_pk_mul_f32 v[18:19], v[18:19], v[64:65]
	v_pk_mul_f32 v[22:23], v[22:23], v[64:65]
	v_pk_mul_f32 v[36:37], v[36:37], v[66:67]
	v_pk_mul_f32 v[38:39], v[38:39], v[64:65]
	v_pk_fma_f32 v[64:65], v[16:17], v[66:67], v[18:19]
	v_pk_fma_f32 v[66:67], v[20:21], v[66:67], v[22:23]
	v_add_f32_e32 v75, v64, v65
	v_add_f32_e32 v64, v66, v67
	v_pk_fma_f32 v[36:37], v[28:29], v[88:89], v[36:37] op_sel:[0,1,0]
	v_pk_fma_f32 v[38:39], v[30:31], v[88:89], v[38:39] op_sel:[0,1,0]
	v_add_f32_dpp v64, v64, v64 quad_perm:[1,0,3,2] row_mask:0xf bank_mask:0xf bound_ctrl:1
	ds_read_b128 v[4:7], v72 offset:24192
	ds_read_b128 v[16:19], v72 offset:24960
	ds_read_b128 v[20:23], v72 offset:25344
	ds_read_b128 v[28:31], v72 offset:26112
	v_add_f32_dpp v64, v64, v64 quad_perm:[2,3,0,1] row_mask:0xf bank_mask:0xf bound_ctrl:1
	s_nop 1
	v_add_f32_dpp v64, v64, v64 row_half_mirror row_mask:0xf bank_mask:0xf bound_ctrl:1
	s_nop 1
	v_add_f32_dpp v64, v64, v64 row_mirror row_mask:0xf bank_mask:0xf bound_ctrl:1
	v_pk_fma_f32 v[66:67], v[24:25], v[64:65], v[36:37] op_sel_hi:[1,0,1]
	v_pk_fma_f32 v[64:65], v[26:27], v[64:65], v[38:39] op_sel_hi:[1,0,1]
	v_pk_mul_f32 v[88:89], v[48:49], v[66:67]
	v_pk_mul_f32 v[34:35], v[34:35], v[64:65]
	v_pk_mul_f32 v[42:43], v[42:43], v[64:65]
	v_pk_fma_f32 v[96:97], v[32:33], v[66:67], v[34:35]
	v_pk_fma_f32 v[66:67], v[40:41], v[66:67], v[42:43]
	v_pk_mul_f32 v[64:65], v[50:51], v[64:65]
	v_add_f32_e32 v66, v66, v67
	v_pk_fma_f32 v[88:89], v[52:53], v[90:91], v[88:89] op_sel_hi:[1,0,1]
	v_pk_fma_f32 v[64:65], v[54:55], v[90:91], v[64:65] op_sel_hi:[1,0,1]
	v_add_f32_dpp v66, v66, v66 quad_perm:[1,0,3,2] row_mask:0xf bank_mask:0xf bound_ctrl:1
	v_add_f32_e32 v90, v96, v97
	v_cndmask_b32_e32 v67, v75, v90, vcc
	v_add_f32_dpp v66, v66, v66 quad_perm:[2,3,0,1] row_mask:0xf bank_mask:0xf bound_ctrl:1
	v_cndmask_b32_e32 v75, v90, v75, vcc
	ds_read_b128 v[24:27], v72 offset:25600
	ds_read_b128 v[36:39], v72 offset:25856
	v_add_f32_dpp v66, v66, v66 row_half_mirror row_mask:0xf bank_mask:0xf bound_ctrl:1
	v_add_f32_dpp v105, v67, v75 quad_perm:[1,0,3,2] row_mask:0xf bank_mask:0xf bound_ctrl:1
	ds_read_b128 v[48:51], v72 offset:27264
	ds_read_b128 v[32:35], v72 offset:26368
	v_add_f32_dpp v66, v66, v66 row_mirror row_mask:0xf bank_mask:0xf bound_ctrl:1
	v_pk_fma_f32 v[64:65], v[46:47], v[66:67], v[64:65] op_sel_hi:[1,0,1]
	v_pk_fma_f32 v[88:89], v[44:45], v[66:67], v[88:89] op_sel_hi:[1,0,1]
	s_waitcnt lgkmcnt(11)
	v_pk_mul_f32 v[66:67], v[94:95], v[64:65]
	v_pk_mul_f32 v[58:59], v[58:59], v[64:65]
	v_pk_fma_f32 v[66:67], v[92:93], v[88:89], v[66:67]
	v_pk_mul_f32 v[64:65], v[78:79], v[64:65]
	v_add_f32_e32 v66, v66, v67
	v_pk_fma_f32 v[78:79], v[56:57], v[88:89], v[58:59]
	v_pk_mul_f32 v[76:77], v[76:77], v[88:89]
	v_add_f32_dpp v66, v66, v66 quad_perm:[1,0,3,2] row_mask:0xf bank_mask:0xf bound_ctrl:1
	v_pk_fma_f32 v[64:65], v[98:99], v[82:83], v[64:65] op_sel_hi:[0,1,1]
	v_add_f32_e32 v104, v78, v79
	v_add_f32_dpp v66, v66, v66 quad_perm:[2,3,0,1] row_mask:0xf bank_mask:0xf bound_ctrl:1
	v_pk_fma_f32 v[76:77], v[98:99], v[80:81], v[76:77] op_sel_hi:[0,1,1]
	ds_read_b128 v[40:43], v72 offset:26752
	ds_read_b128 v[52:55], v72 offset:27520
	v_add_f32_dpp v66, v66, v66 row_half_mirror row_mask:0xf bank_mask:0xf bound_ctrl:1
	ds_read_b128 v[44:47], v72 offset:27008
	ds_read_b128 v[56:59], v72 offset:27776
	v_add_f32_dpp v78, v66, v66 row_mirror row_mask:0xf bank_mask:0xf bound_ctrl:1
	v_pk_fma_f32 v[64:65], v[62:63], v[78:79], v[64:65] op_sel_hi:[1,0,1]
	v_pk_fma_f32 v[66:67], v[60:61], v[78:79], v[76:77] op_sel_hi:[1,0,1]
	v_pk_mul_f32 v[102:103], v[86:87], v[64:65]
	v_pk_fma_f32 v[102:103], v[84:85], v[66:67], v[102:103]
	s_waitcnt lgkmcnt(14)
	v_pk_mul_f32 v[2:3], v[64:65], v[2:3]
	v_add_f32_e32 v102, v102, v103
	ds_read_b128 v[60:63], v72 offset:28416
	v_cndmask_b32_e32 v106, v104, v102, vcc
	v_cndmask_b32_e32 v102, v102, v104, vcc
	ds_read_b128 v[76:79], v72 offset:28672
	ds_read_b128 v[80:83], v72 offset:28928
	ds_read_b128 v[84:87], v72 offset:29184
	ds_read_b128 v[88:91], v100 offset:80
	ds_read_b128 v[92:95], v72 offset:28160
	v_add_f32_dpp v102, v106, v102 quad_perm:[1,0,3,2] row_mask:0xf bank_mask:0xf bound_ctrl:1
	v_pk_fma_f32 v[96:97], v[66:67], v[0:1], v[2:3]
	v_cndmask_b32_e64 v106, v105, v102, s[4:5]
	v_cndmask_b32_e64 v102, v102, v105, s[4:5]
	ds_read_b128 v[0:3], v72 offset:29568
	v_add_f32_e32 v75, v96, v97
	s_waitcnt lgkmcnt(2)
; template <int CTRL> DI float dppf(float v) { return __int_as_float(__builtin_amdgcn_update_dpp(0, __float_as_int(v), CTRL, 0xf, 0xf, false)); }
; DI float red16(float p) { p += dppf<0xB1>(p); p += dppf<0x4E>(p); p += dppf<0x141>(p); p += dppf<0x140>(p); return p; }
; DI void scan_task(const Params& P, int sb, unsigned char* lds) {
;     ...
;         for (int i = 0; i < 4; ++i) {
;           ld_ops(nx3, gb + (i + 3) * SREC, q4);
;           const f2 a01 = {cur.a.x, cur.a.y}, a23 = {cur.a.z, cur.a.w}, w01 = {cur.w.x, cur.w.y}, w23 = {cur.w.z, cur.w.w};
;           const f2 k01 = {cur.k.x, cur.k.y}, k23 = {cur.k.z, cur.k.w}, b01 = {cur.b.x, cur.b.y}, b23 = {cur.b.z, cur.b.w};
;           const f2 r01 = {cur.r.x, cur.r.y}, r23 = {cur.r.z, cur.r.w};
;           f2 pa = S0 * a01; pa += S1 * a23;
;           const float vs = (i == 0) ? v4.x : (i == 1) ? v4.y : (i == 2) ? v4.z : v4.w;
;           const f2 vv = {vs, vs};
;           const f2 t0 = S0 * w01 + vv * k01, t1 = S1 * w23 + vv * k23;
;           const float sa = red16(pa.x + pa.y);
;           const f2 sa2 = {sa, sa};
;           S0 = t0 + sa2 * b01; S1 = t1 + sa2 * b23;
;           f2 py = S0 * r01; py += S1 * r23;
;           pp[i] = py.x + py.y;
;           cur = nxt; nxt = nx2; nx2 = nx3;
;         }
;         const float tA = o1 ? pp[0] : pp[1], kA = o1 ? pp[1] : pp[0];
;         const float tB = o1 ? pp[2] : pp[3], kB = o1 ? pp[3] : pp[2];
;         const float r0 = kA + dppf<0xB1>(tA), r1 = kB + dppf<0xB1>(tB);
;         const float tC = o2 ? r0 : r1, kC = o2 ? r1 : r0;
;         float u = kC + dppf<0x4E>(tC);
;         u += dppf<0x124>(u);
;         u += dppf<0x128>(u);
;         yb[(g4 * 4 + (q & 3)) * 16 + rowl] = u;
	v_add_f32_dpp v102, v106, v102 quad_perm:[2,3,0,1] row_mask:0xf bank_mask:0xf bound_ctrl:1
	v_pk_mul_f32 v[14:15], v[14:15], v[88:89] op_sel_hi:[1,0]
	v_pk_mul_f32 v[12:13], v[12:13], v[88:89] op_sel_hi:[1,0]
	v_add_f32_dpp v102, v102, v102 row_ror:4 row_mask:0xf bank_mask:0xf bound_ctrl:1
	v_add_f32_dpp v75, v75, v75 quad_perm:[1,0,3,2] row_mask:0xf bank_mask:0xf bound_ctrl:1
	v_pk_fma_f32 v[64:65], v[64:65], v[10:11], v[14:15]
	v_pk_fma_f32 v[66:67], v[66:67], v[8:9], v[12:13]
	v_add_f32_dpp v102, v102, v102 row_ror:8 row_mask:0xf bank_mask:0xf bound_ctrl:1
	v_add_f32_dpp v75, v75, v75 quad_perm:[2,3,0,1] row_mask:0xf bank_mask:0xf bound_ctrl:1
	v_mov_b32_e32 v98, v91
	ds_write_b32 v73, v102 offset:1024
	ds_read_b128 v[8:11], v72 offset:30080
	ds_read_b128 v[12:15], v72 offset:30336
	v_add_f32_dpp v75, v75, v75 row_half_mirror row_mask:0xf bank_mask:0xf bound_ctrl:1
	s_nop 1
	v_add_f32_dpp v96, v75, v75 row_mirror row_mask:0xf bank_mask:0xf bound_ctrl:1
	v_pk_fma_f32 v[64:65], v[6:7], v[96:97], v[64:65] op_sel_hi:[1,0,1]
	v_pk_fma_f32 v[66:67], v[4:5], v[96:97], v[66:67] op_sel_hi:[1,0,1]
	v_pk_mul_f32 v[18:19], v[18:19], v[64:65]
	v_pk_mul_f32 v[22:23], v[22:23], v[64:65]
	v_pk_mul_f32 v[36:37], v[36:37], v[66:67]
	v_pk_mul_f32 v[38:39], v[38:39], v[64:65]
	v_pk_fma_f32 v[64:65], v[16:17], v[66:67], v[18:19]
	v_pk_fma_f32 v[66:67], v[20:21], v[66:67], v[22:23]
	v_add_f32_e32 v75, v64, v65
	v_add_f32_e32 v64, v66, v67
	v_pk_fma_f32 v[36:37], v[28:29], v[88:89], v[36:37] op_sel:[0,1,0]
	v_pk_fma_f32 v[38:39], v[30:31], v[88:89], v[38:39] op_sel:[0,1,0]
	v_add_f32_dpp v64, v64, v64 quad_perm:[1,0,3,2] row_mask:0xf bank_mask:0xf bound_ctrl:1
	ds_read_b128 v[4:7], v72 offset:29824
	ds_read_b128 v[16:19], v72 offset:30592
	ds_read_b128 v[20:23], v72 offset:30976
	ds_read_b128 v[28:31], v72 offset:31744
	v_add_f32_dpp v64, v64, v64 quad_perm:[2,3,0,1] row_mask:0xf bank_mask:0xf bound_ctrl:1
	s_nop 1
	v_add_f32_dpp v64, v64, v64 row_half_mirror row_mask:0xf bank_mask:0xf bound_ctrl:1
	s_nop 1
	v_add_f32_dpp v64, v64, v64 row_mirror row_mask:0xf bank_mask:0xf bound_ctrl:1
	v_pk_fma_f32 v[66:67], v[24:25], v[64:65], v[36:37] op_sel_hi:[1,0,1]
	v_pk_fma_f32 v[64:65], v[26:27], v[64:65], v[38:39] op_sel_hi:[1,0,1]
	v_pk_mul_f32 v[88:89], v[48:49], v[66:67]
	v_pk_mul_f32 v[34:35], v[34:35], v[64:65]
	v_pk_mul_f32 v[42:43], v[42:43], v[64:65]
	v_pk_fma_f32 v[96:97], v[32:33], v[66:67], v[34:35]
	v_pk_fma_f32 v[66:67], v[40:41], v[66:67], v[42:43]
	v_pk_mul_f32 v[64:65], v[50:51], v[64:65]
	v_add_f32_e32 v66, v66, v67
	v_pk_fma_f32 v[88:89], v[52:53], v[90:91], v[88:89] op_sel_hi:[1,0,1]
	v_pk_fma_f32 v[64:65], v[54:55], v[90:91], v[64:65] op_sel_hi:[1,0,1]
	v_add_f32_dpp v66, v66, v66 quad_perm:[1,0,3,2] row_mask:0xf bank_mask:0xf bound_ctrl:1
	v_add_f32_e32 v90, v96, v97
	v_cndmask_b32_e32 v67, v75, v90, vcc
	v_add_f32_dpp v66, v66, v66 quad_perm:[2,3,0,1] row_mask:0xf bank_mask:0xf bound_ctrl:1
	v_cndmask_b32_e32 v75, v90, v75, vcc
	ds_read_b128 v[24:27], v72 offset:31232
	ds_read_b128 v[36:39], v72 offset:31488
	v_add_f32_dpp v66, v66, v66 row_half_mirror row_mask:0xf bank_mask:0xf bound_ctrl:1
	v_add_f32_dpp v105, v67, v75 quad_perm:[1,0,3,2] row_mask:0xf bank_mask:0xf bound_ctrl:1
	ds_read_b128 v[48:51], v72 offset:32896
	ds_read_b128 v[32:35], v72 offset:32000
	v_add_f32_dpp v66, v66, v66 row_mirror row_mask:0xf bank_mask:0xf bound_ctrl:1
	v_pk_fma_f32 v[64:65], v[46:47], v[66:67], v[64:65] op_sel_hi:[1,0,1]
	v_pk_fma_f32 v[88:89], v[44:45], v[66:67], v[88:89] op_sel_hi:[1,0,1]
	s_waitcnt lgkmcnt(11)
	v_pk_mul_f32 v[66:67], v[94:95], v[64:65]
	v_pk_mul_f32 v[58:59], v[58:59], v[64:65]
	v_pk_fma_f32 v[66:67], v[92:93], v[88:89], v[66:67]
	v_pk_mul_f32 v[64:65], v[78:79], v[64:65]
	v_add_f32_e32 v66, v66, v67
	v_pk_fma_f32 v[78:79], v[56:57], v[88:89], v[58:59]
	v_pk_mul_f32 v[76:77], v[76:77], v[88:89]
	v_add_f32_dpp v66, v66, v66 quad_perm:[1,0,3,2] row_mask:0xf bank_mask:0xf bound_ctrl:1
	v_pk_fma_f32 v[64:65], v[98:99], v[82:83], v[64:65] op_sel_hi:[0,1,1]
	v_add_f32_e32 v104, v78, v79
	v_add_f32_dpp v66, v66, v66 quad_perm:[2,3,0,1] row_mask:0xf bank_mask:0xf bound_ctrl:1
	v_pk_fma_f32 v[76:77], v[98:99], v[80:81], v[76:77] op_sel_hi:[0,1,1]
	ds_read_b128 v[40:43], v72 offset:32384
	ds_read_b128 v[52:55], v72 offset:33152
	v_add_f32_dpp v66, v66, v66 row_half_mirror row_mask:0xf bank_mask:0xf bound_ctrl:1
	ds_read_b128 v[44:47], v72 offset:32640
	ds_read_b128 v[56:59], v72 offset:33408
	v_add_f32_dpp v78, v66, v66 row_mirror row_mask:0xf bank_mask:0xf bound_ctrl:1
	v_pk_fma_f32 v[64:65], v[62:63], v[78:79], v[64:65] op_sel_hi:[1,0,1]
	v_pk_fma_f32 v[66:67], v[60:61], v[78:79], v[76:77] op_sel_hi:[1,0,1]
	v_pk_mul_f32 v[102:103], v[86:87], v[64:65]
	v_pk_fma_f32 v[102:103], v[84:85], v[66:67], v[102:103]
	s_waitcnt lgkmcnt(14)
	v_pk_mul_f32 v[2:3], v[64:65], v[2:3]
	v_add_f32_e32 v102, v102, v103
	ds_read_b128 v[60:63], v72 offset:34048
	v_cndmask_b32_e32 v106, v104, v102, vcc
	v_cndmask_b32_e32 v102, v102, v104, vcc
	ds_read_b128 v[76:79], v72 offset:34304
	ds_read_b128 v[80:83], v72 offset:34560
	ds_read_b128 v[84:87], v72 offset:34816
	ds_read_b128 v[88:91], v100 offset:96
	ds_read_b128 v[92:95], v72 offset:33792
	v_add_f32_dpp v102, v106, v102 quad_perm:[1,0,3,2] row_mask:0xf bank_mask:0xf bound_ctrl:1
	v_pk_fma_f32 v[96:97], v[66:67], v[0:1], v[2:3]
	v_cndmask_b32_e64 v106, v105, v102, s[4:5]
	v_cndmask_b32_e64 v102, v102, v105, s[4:5]
	ds_read_b128 v[0:3], v72 offset:35200
	v_add_f32_e32 v75, v96, v97
	s_waitcnt lgkmcnt(2)
; template <int CTRL> DI float dppf(float v) { return __int_as_float(__builtin_amdgcn_update_dpp(0, __float_as_int(v), CTRL, 0xf, 0xf, false)); }
; DI float red16(float p) { p += dppf<0xB1>(p); p += dppf<0x4E>(p); p += dppf<0x141>(p); p += dppf<0x140>(p); return p; }
; DI void scan_task(const Params& P, int sb, unsigned char* lds) {
;     ...
;         for (int i = 0; i < 4; ++i) {
;           ld_ops(nx3, gb + (i + 3) * SREC, q4);
;           const f2 a01 = {cur.a.x, cur.a.y}, a23 = {cur.a.z, cur.a.w}, w01 = {cur.w.x, cur.w.y}, w23 = {cur.w.z, cur.w.w};
;           const f2 k01 = {cur.k.x, cur.k.y}, k23 = {cur.k.z, cur.k.w}, b01 = {cur.b.x, cur.b.y}, b23 = {cur.b.z, cur.b.w};
;           const f2 r01 = {cur.r.x, cur.r.y}, r23 = {cur.r.z, cur.r.w};
;           f2 pa = S0 * a01; pa += S1 * a23;
;           const float vs = (i == 0) ? v4.x : (i == 1) ? v4.y : (i == 2) ? v4.z : v4.w;
;           const f2 vv = {vs, vs};
;           const f2 t0 = S0 * w01 + vv * k01, t1 = S1 * w23 + vv * k23;
;           const float sa = red16(pa.x + pa.y);
;           const f2 sa2 = {sa, sa};
;           S0 = t0 + sa2 * b01; S1 = t1 + sa2 * b23;
;           f2 py = S0 * r01; py += S1 * r23;
;           pp[i] = py.x + py.y;
;           cur = nxt; nxt = nx2; nx2 = nx3;
;         }
;         const float tA = o1 ? pp[0] : pp[1], kA = o1 ? pp[1] : pp[0];
;         const float tB = o1 ? pp[2] : pp[3], kB = o1 ? pp[3] : pp[2];
;         const float r0 = kA + dppf<0xB1>(tA), r1 = kB + dppf<0xB1>(tB);
;         const float tC = o2 ? r0 : r1, kC = o2 ? r1 : r0;
;         float u = kC + dppf<0x4E>(tC);
;         u += dppf<0x124>(u);
;         u += dppf<0x128>(u);
;         yb[(g4 * 4 + (q & 3)) * 16 + rowl] = u;
	v_add_f32_dpp v102, v106, v102 quad_perm:[2,3,0,1] row_mask:0xf bank_mask:0xf bound_ctrl:1
	v_pk_mul_f32 v[14:15], v[14:15], v[88:89] op_sel_hi:[1,0]
	v_pk_mul_f32 v[12:13], v[12:13], v[88:89] op_sel_hi:[1,0]
	v_add_f32_dpp v102, v102, v102 row_ror:4 row_mask:0xf bank_mask:0xf bound_ctrl:1
	v_add_f32_dpp v75, v75, v75 quad_perm:[1,0,3,2] row_mask:0xf bank_mask:0xf bound_ctrl:1
	v_pk_fma_f32 v[64:65], v[64:65], v[10:11], v[14:15]
	v_pk_fma_f32 v[66:67], v[66:67], v[8:9], v[12:13]
	v_add_f32_dpp v102, v102, v102 row_ror:8 row_mask:0xf bank_mask:0xf bound_ctrl:1
	v_add_f32_dpp v75, v75, v75 quad_perm:[2,3,0,1] row_mask:0xf bank_mask:0xf bound_ctrl:1
	v_mov_b32_e32 v98, v91
	ds_write_b32 v73, v102 offset:1280
	ds_read_b128 v[8:11], v72 offset:35712
	ds_read_b128 v[12:15], v72 offset:35968
	v_add_f32_dpp v75, v75, v75 row_half_mirror row_mask:0xf bank_mask:0xf bound_ctrl:1
	s_nop 1
	v_add_f32_dpp v96, v75, v75 row_mirror row_mask:0xf bank_mask:0xf bound_ctrl:1
	v_pk_fma_f32 v[64:65], v[6:7], v[96:97], v[64:65] op_sel_hi:[1,0,1]
	v_pk_fma_f32 v[66:67], v[4:5], v[96:97], v[66:67] op_sel_hi:[1,0,1]
	v_pk_mul_f32 v[18:19], v[18:19], v[64:65]
	v_pk_mul_f32 v[22:23], v[22:23], v[64:65]
	v_pk_mul_f32 v[36:37], v[36:37], v[66:67]
	v_pk_mul_f32 v[38:39], v[38:39], v[64:65]
	v_pk_fma_f32 v[64:65], v[16:17], v[66:67], v[18:19]
	v_pk_fma_f32 v[66:67], v[20:21], v[66:67], v[22:23]
	v_add_f32_e32 v75, v64, v65
	v_add_f32_e32 v64, v66, v67
	v_pk_fma_f32 v[36:37], v[28:29], v[88:89], v[36:37] op_sel:[0,1,0]
	v_pk_fma_f32 v[38:39], v[30:31], v[88:89], v[38:39] op_sel:[0,1,0]
	v_add_f32_dpp v64, v64, v64 quad_perm:[1,0,3,2] row_mask:0xf bank_mask:0xf bound_ctrl:1
	ds_read_b128 v[4:7], v72 offset:35456
	ds_read_b128 v[16:19], v72 offset:36224
	ds_read_b128 v[20:23], v72 offset:36608
	ds_read_b128 v[28:31], v72 offset:37376
	v_add_f32_dpp v64, v64, v64 quad_perm:[2,3,0,1] row_mask:0xf bank_mask:0xf bound_ctrl:1
	s_nop 1
	v_add_f32_dpp v64, v64, v64 row_half_mirror row_mask:0xf bank_mask:0xf bound_ctrl:1
	s_nop 1
	v_add_f32_dpp v64, v64, v64 row_mirror row_mask:0xf bank_mask:0xf bound_ctrl:1
	v_pk_fma_f32 v[66:67], v[24:25], v[64:65], v[36:37] op_sel_hi:[1,0,1]
	v_pk_fma_f32 v[64:65], v[26:27], v[64:65], v[38:39] op_sel_hi:[1,0,1]
	v_pk_mul_f32 v[88:89], v[48:49], v[66:67]
	v_pk_mul_f32 v[34:35], v[34:35], v[64:65]
	v_pk_mul_f32 v[42:43], v[42:43], v[64:65]
	v_pk_fma_f32 v[96:97], v[32:33], v[66:67], v[34:35]
	v_pk_fma_f32 v[66:67], v[40:41], v[66:67], v[42:43]
	v_pk_mul_f32 v[64:65], v[50:51], v[64:65]
	v_add_f32_e32 v66, v66, v67
	v_pk_fma_f32 v[88:89], v[52:53], v[90:91], v[88:89] op_sel_hi:[1,0,1]
	v_pk_fma_f32 v[64:65], v[54:55], v[90:91], v[64:65] op_sel_hi:[1,0,1]
	v_add_f32_dpp v66, v66, v66 quad_perm:[1,0,3,2] row_mask:0xf bank_mask:0xf bound_ctrl:1
	v_add_f32_e32 v90, v96, v97
	v_cndmask_b32_e32 v67, v75, v90, vcc
	v_add_f32_dpp v66, v66, v66 quad_perm:[2,3,0,1] row_mask:0xf bank_mask:0xf bound_ctrl:1
	v_cndmask_b32_e32 v75, v90, v75, vcc
	ds_read_b128 v[24:27], v72 offset:36864
	ds_read_b128 v[36:39], v72 offset:37120
	v_add_f32_dpp v66, v66, v66 row_half_mirror row_mask:0xf bank_mask:0xf bound_ctrl:1
	v_add_f32_dpp v105, v67, v75 quad_perm:[1,0,3,2] row_mask:0xf bank_mask:0xf bound_ctrl:1
	ds_read_b128 v[48:51], v72 offset:38528
	ds_read_b128 v[32:35], v72 offset:37632
	v_add_f32_dpp v66, v66, v66 row_mirror row_mask:0xf bank_mask:0xf bound_ctrl:1
	v_pk_fma_f32 v[64:65], v[46:47], v[66:67], v[64:65] op_sel_hi:[1,0,1]
	v_pk_fma_f32 v[88:89], v[44:45], v[66:67], v[88:89] op_sel_hi:[1,0,1]
	s_waitcnt lgkmcnt(11)
	v_pk_mul_f32 v[66:67], v[94:95], v[64:65]
	v_pk_mul_f32 v[58:59], v[58:59], v[64:65]
	v_pk_fma_f32 v[66:67], v[92:93], v[88:89], v[66:67]
	v_pk_mul_f32 v[64:65], v[78:79], v[64:65]
	v_add_f32_e32 v66, v66, v67
	v_pk_fma_f32 v[78:79], v[56:57], v[88:89], v[58:59]
	v_pk_mul_f32 v[76:77], v[76:77], v[88:89]
	v_add_f32_dpp v66, v66, v66 quad_perm:[1,0,3,2] row_mask:0xf bank_mask:0xf bound_ctrl:1
	v_pk_fma_f32 v[64:65], v[98:99], v[82:83], v[64:65] op_sel_hi:[0,1,1]
	v_add_f32_e32 v104, v78, v79
	v_add_f32_dpp v66, v66, v66 quad_perm:[2,3,0,1] row_mask:0xf bank_mask:0xf bound_ctrl:1
	v_pk_fma_f32 v[76:77], v[98:99], v[80:81], v[76:77] op_sel_hi:[0,1,1]
	ds_read_b128 v[40:43], v72 offset:38016
	ds_read_b128 v[52:55], v72 offset:38784
	v_add_f32_dpp v66, v66, v66 row_half_mirror row_mask:0xf bank_mask:0xf bound_ctrl:1
	ds_read_b128 v[44:47], v72 offset:38272
	ds_read_b128 v[56:59], v72 offset:39040
	v_add_f32_dpp v78, v66, v66 row_mirror row_mask:0xf bank_mask:0xf bound_ctrl:1
	v_pk_fma_f32 v[64:65], v[62:63], v[78:79], v[64:65] op_sel_hi:[1,0,1]
	v_pk_fma_f32 v[66:67], v[60:61], v[78:79], v[76:77] op_sel_hi:[1,0,1]
	v_pk_mul_f32 v[102:103], v[86:87], v[64:65]
	v_pk_fma_f32 v[102:103], v[84:85], v[66:67], v[102:103]
	s_waitcnt lgkmcnt(14)
	v_pk_mul_f32 v[2:3], v[64:65], v[2:3]
	v_add_f32_e32 v102, v102, v103
	ds_read_b128 v[60:63], v72 offset:39680
	v_cndmask_b32_e32 v106, v104, v102, vcc
	v_cndmask_b32_e32 v102, v102, v104, vcc
	ds_read_b128 v[76:79], v72 offset:39936
	ds_read_b128 v[80:83], v72 offset:40192
	ds_read_b128 v[84:87], v72 offset:40448
	ds_read_b128 v[88:91], v100 offset:112
	ds_read_b128 v[92:95], v72 offset:39424
	v_add_f32_dpp v102, v106, v102 quad_perm:[1,0,3,2] row_mask:0xf bank_mask:0xf bound_ctrl:1
	v_pk_fma_f32 v[96:97], v[66:67], v[0:1], v[2:3]
	v_cndmask_b32_e64 v106, v105, v102, s[4:5]
	v_cndmask_b32_e64 v102, v102, v105, s[4:5]
	ds_read_b128 v[0:3], v72 offset:40832
	v_add_f32_e32 v75, v96, v97
	s_waitcnt lgkmcnt(2)
; template <int CTRL> DI float dppf(float v) { return __int_as_float(__builtin_amdgcn_update_dpp(0, __float_as_int(v), CTRL, 0xf, 0xf, false)); }
; DI float red16(float p) { p += dppf<0xB1>(p); p += dppf<0x4E>(p); p += dppf<0x141>(p); p += dppf<0x140>(p); return p; }
; DI void scan_task(const Params& P, int sb, unsigned char* lds) {
;     ...
;         for (int i = 0; i < 4; ++i) {
;           ld_ops(nx3, gb + (i + 3) * SREC, q4);
;           const f2 a01 = {cur.a.x, cur.a.y}, a23 = {cur.a.z, cur.a.w}, w01 = {cur.w.x, cur.w.y}, w23 = {cur.w.z, cur.w.w};
;           const f2 k01 = {cur.k.x, cur.k.y}, k23 = {cur.k.z, cur.k.w}, b01 = {cur.b.x, cur.b.y}, b23 = {cur.b.z, cur.b.w};
;           const f2 r01 = {cur.r.x, cur.r.y}, r23 = {cur.r.z, cur.r.w};
;           f2 pa = S0 * a01; pa += S1 * a23;
;           const float vs = (i == 0) ? v4.x : (i == 1) ? v4.y : (i == 2) ? v4.z : v4.w;
;           const f2 vv = {vs, vs};
;           const f2 t0 = S0 * w01 + vv * k01, t1 = S1 * w23 + vv * k23;
;           const float sa = red16(pa.x + pa.y);
;           const f2 sa2 = {sa, sa};
;           S0 = t0 + sa2 * b01; S1 = t1 + sa2 * b23;
;           f2 py = S0 * r01; py += S1 * r23;
;           pp[i] = py.x + py.y;
;           cur = nxt; nxt = nx2; nx2 = nx3;
;         }
;         const float tA = o1 ? pp[0] : pp[1], kA = o1 ? pp[1] : pp[0];
;         const float tB = o1 ? pp[2] : pp[3], kB = o1 ? pp[3] : pp[2];
;         const float r0 = kA + dppf<0xB1>(tA), r1 = kB + dppf<0xB1>(tB);
;         const float tC = o2 ? r0 : r1, kC = o2 ? r1 : r0;
;         float u = kC + dppf<0x4E>(tC);
;         u += dppf<0x124>(u);
;         u += dppf<0x128>(u);
;         yb[(g4 * 4 + (q & 3)) * 16 + rowl] = u;
;       }
;       __syncthreads();
	v_add_f32_dpp v102, v106, v102 quad_perm:[2,3,0,1] row_mask:0xf bank_mask:0xf bound_ctrl:1
	v_pk_mul_f32 v[14:15], v[14:15], v[88:89] op_sel_hi:[1,0]
	v_pk_mul_f32 v[12:13], v[12:13], v[88:89] op_sel_hi:[1,0]
	v_add_f32_dpp v102, v102, v102 row_ror:4 row_mask:0xf bank_mask:0xf bound_ctrl:1
	v_add_f32_dpp v75, v75, v75 quad_perm:[1,0,3,2] row_mask:0xf bank_mask:0xf bound_ctrl:1
	v_pk_fma_f32 v[64:65], v[64:65], v[10:11], v[14:15]
	v_pk_fma_f32 v[66:67], v[66:67], v[8:9], v[12:13]
	v_add_f32_dpp v102, v102, v102 row_ror:8 row_mask:0xf bank_mask:0xf bound_ctrl:1
	v_add_f32_dpp v75, v75, v75 quad_perm:[2,3,0,1] row_mask:0xf bank_mask:0xf bound_ctrl:1
	v_mov_b32_e32 v98, v91
	ds_write_b32 v73, v102 offset:1536
	ds_read_b128 v[8:11], v72 offset:41344
	ds_read_b128 v[12:15], v72 offset:41600
	v_add_f32_dpp v75, v75, v75 row_half_mirror row_mask:0xf bank_mask:0xf bound_ctrl:1
	s_nop 1
	v_add_f32_dpp v96, v75, v75 row_mirror row_mask:0xf bank_mask:0xf bound_ctrl:1
	v_pk_fma_f32 v[64:65], v[6:7], v[96:97], v[64:65] op_sel_hi:[1,0,1]
	v_pk_fma_f32 v[66:67], v[4:5], v[96:97], v[66:67] op_sel_hi:[1,0,1]
	v_pk_mul_f32 v[18:19], v[18:19], v[64:65]
	v_pk_mul_f32 v[22:23], v[22:23], v[64:65]
	v_pk_mul_f32 v[36:37], v[36:37], v[66:67]
	v_pk_mul_f32 v[38:39], v[38:39], v[64:65]
	v_pk_fma_f32 v[64:65], v[16:17], v[66:67], v[18:19]
	v_pk_fma_f32 v[66:67], v[20:21], v[66:67], v[22:23]
	v_add_f32_e32 v75, v64, v65
	v_add_f32_e32 v64, v66, v67
	v_pk_fma_f32 v[36:37], v[28:29], v[88:89], v[36:37] op_sel:[0,1,0]
	v_pk_fma_f32 v[38:39], v[30:31], v[88:89], v[38:39] op_sel:[0,1,0]
	v_add_f32_dpp v64, v64, v64 quad_perm:[1,0,3,2] row_mask:0xf bank_mask:0xf bound_ctrl:1
	ds_read_b128 v[4:7], v72 offset:41088
	ds_read_b128 v[16:19], v72 offset:41856
	ds_read_b128 v[20:23], v72 offset:42240
	ds_read_b128 v[28:31], v72 offset:43008
	v_add_f32_dpp v64, v64, v64 quad_perm:[2,3,0,1] row_mask:0xf bank_mask:0xf bound_ctrl:1
	s_nop 1
	v_add_f32_dpp v64, v64, v64 row_half_mirror row_mask:0xf bank_mask:0xf bound_ctrl:1
	s_nop 1
	v_add_f32_dpp v64, v64, v64 row_mirror row_mask:0xf bank_mask:0xf bound_ctrl:1
	v_pk_fma_f32 v[66:67], v[24:25], v[64:65], v[36:37] op_sel_hi:[1,0,1]
	v_pk_fma_f32 v[64:65], v[26:27], v[64:65], v[38:39] op_sel_hi:[1,0,1]
	v_pk_mul_f32 v[88:89], v[48:49], v[66:67]
	v_pk_mul_f32 v[34:35], v[34:35], v[64:65]
	v_pk_mul_f32 v[42:43], v[42:43], v[64:65]
	v_pk_fma_f32 v[96:97], v[32:33], v[66:67], v[34:35]
	v_pk_fma_f32 v[66:67], v[40:41], v[66:67], v[42:43]
	v_pk_mul_f32 v[64:65], v[50:51], v[64:65]
	v_add_f32_e32 v66, v66, v67
	v_pk_fma_f32 v[88:89], v[52:53], v[90:91], v[88:89] op_sel_hi:[1,0,1]
	v_pk_fma_f32 v[64:65], v[54:55], v[90:91], v[64:65] op_sel_hi:[1,0,1]
	v_add_f32_dpp v66, v66, v66 quad_perm:[1,0,3,2] row_mask:0xf bank_mask:0xf bound_ctrl:1
	v_add_f32_e32 v90, v96, v97
	v_cndmask_b32_e32 v67, v75, v90, vcc
	v_add_f32_dpp v66, v66, v66 quad_perm:[2,3,0,1] row_mask:0xf bank_mask:0xf bound_ctrl:1
	v_cndmask_b32_e32 v75, v90, v75, vcc
	ds_read_b128 v[24:27], v72 offset:42496
	ds_read_b128 v[36:39], v72 offset:42752
	v_add_f32_dpp v66, v66, v66 row_half_mirror row_mask:0xf bank_mask:0xf bound_ctrl:1
	v_add_f32_dpp v105, v67, v75 quad_perm:[1,0,3,2] row_mask:0xf bank_mask:0xf bound_ctrl:1
	ds_read_b128 v[48:51], v72 offset:44160
	ds_read_b128 v[32:35], v72 offset:43264
	v_add_f32_dpp v66, v66, v66 row_mirror row_mask:0xf bank_mask:0xf bound_ctrl:1
	v_pk_fma_f32 v[64:65], v[46:47], v[66:67], v[64:65] op_sel_hi:[1,0,1]
	v_pk_fma_f32 v[88:89], v[44:45], v[66:67], v[88:89] op_sel_hi:[1,0,1]
	s_waitcnt lgkmcnt(11)
	v_pk_mul_f32 v[66:67], v[94:95], v[64:65]
	v_pk_mul_f32 v[58:59], v[58:59], v[64:65]
	v_pk_fma_f32 v[66:67], v[92:93], v[88:89], v[66:67]
	v_pk_mul_f32 v[64:65], v[78:79], v[64:65]
	v_add_f32_e32 v66, v66, v67
	v_pk_fma_f32 v[78:79], v[56:57], v[88:89], v[58:59]
	v_pk_mul_f32 v[76:77], v[76:77], v[88:89]
	v_add_f32_dpp v66, v66, v66 quad_perm:[1,0,3,2] row_mask:0xf bank_mask:0xf bound_ctrl:1
	v_pk_fma_f32 v[64:65], v[98:99], v[82:83], v[64:65] op_sel_hi:[0,1,1]
	v_add_f32_e32 v104, v78, v79
	v_add_f32_dpp v66, v66, v66 quad_perm:[2,3,0,1] row_mask:0xf bank_mask:0xf bound_ctrl:1
	v_pk_fma_f32 v[76:77], v[98:99], v[80:81], v[76:77] op_sel_hi:[0,1,1]
	ds_read_b128 v[40:43], v72 offset:43648
	ds_read_b128 v[52:55], v72 offset:44416
	v_add_f32_dpp v66, v66, v66 row_half_mirror row_mask:0xf bank_mask:0xf bound_ctrl:1
	ds_read_b128 v[44:47], v72 offset:43904
	ds_read_b128 v[56:59], v72 offset:44672
	v_add_f32_dpp v78, v66, v66 row_mirror row_mask:0xf bank_mask:0xf bound_ctrl:1
	v_pk_fma_f32 v[64:65], v[62:63], v[78:79], v[64:65] op_sel_hi:[1,0,1]
	v_pk_fma_f32 v[66:67], v[60:61], v[78:79], v[76:77] op_sel_hi:[1,0,1]
	v_pk_mul_f32 v[102:103], v[86:87], v[64:65]
	v_pk_fma_f32 v[102:103], v[84:85], v[66:67], v[102:103]
	s_nop 0
	v_add_f32_e32 v102, v102, v103
	v_cndmask_b32_e32 v106, v104, v102, vcc
	v_cndmask_b32_e32 v102, v102, v104, vcc
	s_nop 1
	v_add_f32_dpp v102, v106, v102 quad_perm:[1,0,3,2] row_mask:0xf bank_mask:0xf bound_ctrl:1
	v_cndmask_b32_e64 v106, v105, v102, s[4:5]
	v_cndmask_b32_e64 v102, v102, v105, s[4:5]
	s_nop 1
	v_add_f32_dpp v102, v106, v102 quad_perm:[2,3,0,1] row_mask:0xf bank_mask:0xf bound_ctrl:1
	s_nop 1
	v_add_f32_dpp v102, v102, v102 row_ror:4 row_mask:0xf bank_mask:0xf bound_ctrl:1
	s_nop 1
	v_add_f32_dpp v102, v102, v102 row_ror:8 row_mask:0xf bank_mask:0xf bound_ctrl:1
	ds_write_b32 v73, v102 offset:1792
	s_add_i32 s0, s0, 1
	s_xor_b64 s[6:7], s[6:7], -1
	s_cmpk_eq_i32 s0, 0x108
	s_waitcnt lgkmcnt(0)
	s_barrier
	s_cbranch_scc0 .LBB0_1197
	s_mov_b64 s[4:5], 0

; #define TLOAD(kt) do { const int key0 = (kt) * 64; \
;     rk = *(const uint4*)(KN + (size_t)(key0 + (tid >> 3)) * 64 + (tid & 7) * 8); \
;     if (tid < 256) rr = *(const uint4*)(KR + (size_t)(key0 + (tid >> 2)) * 32 + (tid & 3) * 8); \
;     rv = *(const uint4*)(VT + (size_t)(tid >> 3) * LK + key0 + (tid & 7) * 8); } while (0)
; #define TSTORE(st) do { bf16_t* Ks = Kl + (st) * KB; \
;     *(uint4*)(Ks + (tid >> 3) * AK_LD + (tid & 7) * 8) = rk; \
;     if (tid < 256) *(uint4*)(Ks + (tid >> 2) * AK_LD + 64 + (tid & 3) * 8) = rr; \
;     *(uint4*)(Vl + (st) * VB + (tid >> 3) * AV_LD + (tid & 7) * 8) = rv; } while (0)
; DI void attn_item(const Params& P, int item, unsigned char* lds) {
;     ...
;   f32x16 O00, O01, O10, O11;
; #pragma unroll
;   for (int e = 0; e < 16; ++e) { O00[e] = 0.f; O01[e] = 0.f; O10[e] = 0.f; O11[e] = 0.f; }
;   float m0 = -1e30f, l0 = 0.f, m1 = -1e30f, l1 = 0.f;
;   constexpr int KB = 64 * AK_LD, VB = 64 * AV_LD;
;   bf16_t* Kl = (bf16_t*)lds; bf16_t* Vl = Kl + 2 * KB;
;   uint4 rk, rr = make_uint4(0, 0, 0, 0), rv;
;     ...
;   const int NKT = LK / 64;
;   __syncthreads();
;   TLOAD(0); TSTORE(0);
;   __syncthreads();
.LBB0_1245:
	s_or_b64 exec, exec, s[26:27]
	s_add_u32 s26, s3, s45
	s_addc_u32 s27, s28, s44
	v_mov_b64_e32 v[0:1], s[26:27]
	v_mad_i64_i32 v[0:1], s[26:27], v8, s36, v[0:1]
	v_lshl_add_u64 v[196:197], v[0:1], 0, v[188:189]
	global_load_dwordx4 v[0:3], v[196:197], off
	v_mul_lo_u32 v195, v8, s37
	v_lshl_add_u32 v214, v195, 1, v188
	s_waitcnt vmcnt(1)
	ds_write_b128 v214, v[4:7]
	s_and_saveexec_b64 s[26:27], vcc
	s_xor_b64 s[26:27], exec, s[26:27]
	v_lshrrev_b32_e32 v198, 2, v10
	v_and_b32_e32 v194, 24, v12
	v_mul_lo_u32 v215, v198, s38
	s_andn2_saveexec_b64 s[26:27], s[26:27]
	v_mul_lo_u32 v215, v198, s38
	v_lshl_add_u32 v4, v194, 1, v215
	ds_write_b128 v4, v[128:131] offset:128
	s_or_b64 exec, exec, s[26:27]
	v_mul_lo_u32 v6, v8, s39
	v_lshlrev_b32_e32 v190, 3, v11
	v_lshl_add_u32 v213, v9, 1, v6
	s_waitcnt vmcnt(0)
	ds_write_b128 v213, v[0:3] offset:26624
	v_lshlrev_b32_e32 v0, 1, v190
	v_mad_u32_u24 v219, v191, s38, v0
	v_lshlrev_b32_e32 v0, 6, v191
	v_ashrrev_i32_e32 v199, 31, v198
	s_ashr_i32 s19, s18, 31
	v_sub_u32_e32 v216, v219, v0
	v_lshlrev_b64 v[0:1], 6, v[198:199]
	v_lshl_add_u64 v[0:1], s[24:25], 0, v[0:1]
	v_and_b32_e32 v2, 3, v10
	s_add_u32 s24, s45, 0xcef0080
	v_mad_i64_i32 v[4:5], s[26:27], v8, s36, 0
	v_lshlrev_b32_e32 v2, 4, v2
	v_mov_b32_e32 v3, v189
	s_addc_u32 s25, s44, 0
	v_lshl_add_u64 v[202:203], v[0:1], 0, v[2:3]
	v_lshl_add_u64 v[0:1], s[24:25], 0, v[4:5]
	v_and_b32_e32 v2, 7, v10
	s_add_u32 s24, s45, 0xbe72000
	v_lshlrev_b32_e32 v2, 4, v2
	s_addc_u32 s25, s44, 0
	v_lshl_add_u64 v[204:205], v[0:1], 0, v[2:3]
	v_lshl_add_u64 v[0:1], s[24:25], 0, v[200:201]
	v_mov_b32_e32 v48, v189
	v_mov_b32_e32 v49, v189
	v_lshl_add_u64 v[206:207], v[0:1], 0, v[2:3]
	v_mov_b32_e32 v50, v189
	v_mov_b32_e32 v51, v189
	v_mov_b32_e32 v52, v189
	v_mov_b32_e32 v53, v189
	v_mov_b32_e32 v54, v189
	v_mov_b32_e32 v55, v189
	v_mov_b32_e32 v56, v189
	v_mov_b32_e32 v57, v189
	v_mov_b32_e32 v58, v189
	v_mov_b32_e32 v59, v189
	v_mov_b32_e32 v60, v189
	v_mov_b32_e32 v61, v189
	v_mov_b32_e32 v62, v189
	v_mov_b32_e32 v63, v189
	v_mov_b64_e32 v[32:33], v[48:49]
	v_mov_b64_e32 v[16:17], v[48:49]
	v_mov_b64_e32 v[0:1], v[48:49]
	s_mov_b32 s26, 0
	v_mbcnt_lo_u32_b32 v244, -1, 0
	v_mbcnt_hi_u32_b32 v244, -1, v244
	v_cmp_gt_u32_e32 vcc, 32, v244
	v_mov_b32_e32 v245, 0
	v_mov_b32_e32 v247, 0x3f80
	v_mov_b32_e32 v246, 0
	v_cndmask_b32_e32 v244, v245, v247, vcc
	v_mov_b32_e32 v247, 0
	v_mov_b32_e32 v248, 0
	v_mov_b32_e32 v249, 0
	v_mov_b32_e32 v250, 0
	v_mov_b32_e32 v251, 0
	v_mov_b32_e32 v252, 0
	v_mov_b32_e32 v253, 0
	v_mov_b32_e32 v254, 0
	v_mov_b32_e32 v255, 0
	v_mov_b32_e32 v218, 0
	v_mov_b32_e32 v212, 0
	v_mov_b32_e32 v193, 0
	v_mov_b64_e32 v[34:35], v[50:51]
	v_mov_b64_e32 v[36:37], v[52:53]
	v_mov_b64_e32 v[38:39], v[54:55]
	v_mov_b64_e32 v[40:41], v[56:57]
	v_mov_b64_e32 v[42:43], v[58:59]
	v_mov_b64_e32 v[44:45], v[60:61]
	v_mov_b64_e32 v[46:47], v[62:63]
	v_mov_b64_e32 v[18:19], v[50:51]
	v_mov_b64_e32 v[20:21], v[52:53]
	v_mov_b64_e32 v[22:23], v[54:55]
	v_mov_b64_e32 v[24:25], v[56:57]
	v_mov_b64_e32 v[26:27], v[58:59]
	v_mov_b64_e32 v[28:29], v[60:61]
	v_mov_b64_e32 v[30:31], v[62:63]
	v_mov_b64_e32 v[2:3], v[50:51]
	v_mov_b64_e32 v[4:5], v[52:53]
	v_mov_b64_e32 v[6:7], v[54:55]
	v_mov_b64_e32 v[8:9], v[56:57]
	v_mov_b64_e32 v[10:11], v[58:59]
	v_mov_b64_e32 v[12:13], v[60:61]
	v_mov_b64_e32 v[14:15], v[62:63]
	v_mov_b32_e32 v217, 0
	s_waitcnt lgkmcnt(0)
	s_barrier
	s_branch .LBB0_1251
.LBB0_1250:
	s_mulk_i32 s27, 0x2400
	v_add_u32_e32 v64, s27, v213
	v_lshl_add_u64 v[202:203], v[202:203], 0, s[12:13]
	v_lshl_add_u64 v[204:205], v[204:205], 0, s[14:15]
	s_cmpk_eq_i32 s26, 0x83
	v_lshl_add_u64 v[206:207], v[206:207], 0, s[16:17]
	s_waitcnt vmcnt(0)
	ds_write_b128 v64, v[184:187] offset:26624
	s_waitcnt lgkmcnt(0)
	s_barrier
	s_cbranch_scc1 .LBB0_1259

; #define TLOAD(kt) do { const int key0 = (kt) * 64; \
;     rk = *(const uint4*)(KN + (size_t)(key0 + (tid >> 3)) * 64 + (tid & 7) * 8); \
;     if (tid < 256) rr = *(const uint4*)(KR + (size_t)(key0 + (tid >> 2)) * 32 + (tid & 3) * 8); \
;     rv = *(const uint4*)(VT + (size_t)(tid >> 3) * LK + key0 + (tid & 7) * 8); } while (0)
; #define TSTORE(st) do { bf16_t* Ks = Kl + (st) * KB; \
;     *(uint4*)(Ks + (tid >> 3) * AK_LD + (tid & 7) * 8) = rk; \
;     if (tid < 256) *(uint4*)(Ks + (tid >> 2) * AK_LD + 64 + (tid & 3) * 8) = rr; \
;     *(uint4*)(Vl + (st) * VB + (tid >> 3) * AV_LD + (tid & 7) * 8) = rv; } while (0)
; #define QKSTEP(off, qa, qbb) do { const bf16x8 a0 = *(const bf16x8*)(kp + (off)), a1 = *(const bf16x8*)(kp + 32 * AK_LD + (off)); \
;       s00 = MF(a0, qa, s00); s01 = MF(a1, qa, s01); s10 = MF(a0, qbb, s10); s11 = MF(a1, qbb, s11); } while (0)
; DI void attn_item(const Params& P, int item, unsigned char* lds) {
;     ...
;   const int NKT = LK / 64;
;   __syncthreads();
;   TLOAD(0); TSTORE(0);
;   __syncthreads();
;   for (int kt = 0; kt < NKT; ++kt) {
;     { const int k1 = (kt + 1 < NKT) ? kt + 1 : NKT - 1; TLOAD(k1); }
;     const bf16_t* Ks = Kl + (kt & 1) * KB; const bf16_t* Vs = Vl + (kt & 1) * VB;
;     f32x16 s00, s01, s10, s11;
; #pragma unroll
;     for (int e = 0; e < 16; ++e) { s00[e] = 0.f; s01[e] = 0.f; s10[e] = 0.f; s11[e] = 0.f; }
;     const bf16_t* kp = Ks + l31 * AK_LD + hh * 8;
;     ...
;     QKSTEP(0, qa0, qb0); QKSTEP(16, qa1, qb1); QKSTEP(32, qa2, qb2); QKSTEP(48, qa3, qb3); QKSTEP(64, qa4, qb4); QKSTEP(80, qa5, qb5);
;     ...
;     SOFTMAX(s00, s01, m0, l0, O00, O01);
;     SOFTMAX(s10, s11, m1, l1, O10, O11);
.LBB0_1253:
	s_or_b64 exec, exec, s[24:25]
	s_and_b32 s24, s26, 1
	s_mul_i32 s25, s24, 0x3400
	v_add_u32_e32 v72, s25, v219
	ds_read_b128 v[64:67], v72
	ds_read_b128 v[68:71], v72 offset:32
	v_lshl_add_u64 v[236:237], s[94:95], 0, v[204:205]
	s_waitcnt lgkmcnt(1)
	v_mfma_f32_32x32x16_bf16 v[112:127], v[64:67], v[176:179], 0
	v_mfma_f32_32x32x16_bf16 v[96:111], v[64:67], v[152:155], 0
	s_waitcnt lgkmcnt(0)
	v_mfma_f32_32x32x16_bf16 v[112:127], v[68:71], v[172:175], v[112:127]
	v_mfma_f32_32x32x16_bf16 v[96:111], v[68:71], v[148:151], v[96:111]
	ds_read_b128 v[64:67], v72 offset:64
	ds_read_b128 v[68:71], v72 offset:96
	s_waitcnt lgkmcnt(1)
	v_mfma_f32_32x32x16_bf16 v[112:127], v[64:67], v[168:171], v[112:127]
	v_mfma_f32_32x32x16_bf16 v[96:111], v[64:67], v[144:147], v[96:111]
	s_waitcnt lgkmcnt(0)
	v_mfma_f32_32x32x16_bf16 v[112:127], v[68:71], v[164:167], v[112:127]
	v_mfma_f32_32x32x16_bf16 v[96:111], v[68:71], v[140:143], v[96:111]
	ds_read_b128 v[64:67], v72 offset:128
	ds_read_b128 v[68:71], v72 offset:160
	s_waitcnt lgkmcnt(1)
	v_mfma_f32_32x32x16_bf16 v[112:127], v[64:67], v[160:163], v[112:127]
	v_mfma_f32_32x32x16_bf16 v[96:111], v[64:67], v[136:139], v[96:111]
	ds_read_b128 v[64:67], v72 offset:6656
	ds_read_b128 v[184:187], v72 offset:6688
	ds_read_b128 v[220:223], v72 offset:6720
	ds_read_b128 v[224:227], v72 offset:6752
	ds_read_b128 v[228:231], v72 offset:6784
	ds_read_b128 v[232:235], v72 offset:6816
	s_waitcnt lgkmcnt(6)
	v_mfma_f32_32x32x16_bf16 v[112:127], v[68:71], v[156:159], v[112:127]
	v_mfma_f32_32x32x16_bf16 v[112:127], v[244:247], v[248:251], v[112:127]
	v_mfma_f32_32x32x16_bf16 v[96:111], v[68:71], v[132:135], v[96:111]
	v_mfma_f32_32x32x16_bf16 v[96:111], v[244:247], v[252:255], v[96:111]
	s_waitcnt lgkmcnt(5)
	v_mfma_f32_32x32x16_bf16 v[80:95], v[64:67], v[176:179], 0
	v_mfma_f32_32x32x16_bf16 v[64:79], v[64:67], v[152:155], 0
	s_waitcnt lgkmcnt(4)
	v_mfma_f32_32x32x16_bf16 v[80:95], v[184:187], v[172:175], v[80:95]
	v_mfma_f32_32x32x16_bf16 v[64:79], v[184:187], v[148:151], v[64:79]
	global_load_dwordx4 v[184:187], v[236:237], off
	s_nop 3
	v_max_f32_e32 v236, v113, v113
	v_max_f32_e32 v237, v112, v112
	v_max_f32_e32 v236, v237, v236
	v_max3_f32 v236, v236, v114, v115
	s_waitcnt lgkmcnt(3)
	v_mfma_f32_32x32x16_bf16 v[80:95], v[220:223], v[168:171], v[80:95]
	s_waitcnt lgkmcnt(2)
	v_mfma_f32_32x32x16_bf16 v[80:95], v[224:227], v[164:167], v[80:95]
	v_mfma_f32_32x32x16_bf16 v[64:79], v[220:223], v[144:147], v[64:79]
	v_max3_f32 v220, v236, v116, v117
	v_max3_f32 v220, v220, v118, v119
	v_max3_f32 v220, v220, v120, v121
	v_max3_f32 v220, v220, v122, v123
	v_max3_f32 v220, v220, v124, v125
	v_max3_f32 v220, v220, v126, v127
	s_waitcnt lgkmcnt(1)
	v_mfma_f32_32x32x16_bf16 v[80:95], v[228:231], v[160:163], v[80:95]
	v_mfma_f32_32x32x16_bf16 v[64:79], v[224:227], v[140:143], v[64:79]
	s_waitcnt lgkmcnt(0)
	v_mfma_f32_32x32x16_bf16 v[80:95], v[232:235], v[156:159], v[80:95]
	v_mfma_f32_32x32x16_bf16 v[80:95], v[244:247], v[248:251], v[80:95]
	v_mfma_f32_32x32x16_bf16 v[64:79], v[228:231], v[136:139], v[64:79]
	s_nop 10
	v_max3_f32 v220, v220, v80, v81
	v_max3_f32 v220, v220, v82, v83
	v_max3_f32 v220, v220, v84, v85
	v_max3_f32 v220, v220, v86, v87
	v_max3_f32 v220, v220, v88, v89
	v_max3_f32 v220, v220, v90, v91
	v_max3_f32 v220, v220, v92, v93
	v_mfma_f32_32x32x16_bf16 v[64:79], v[232:235], v[132:135], v[64:79]
	v_mfma_f32_32x32x16_bf16 v[64:79], v[244:247], v[252:255], v[64:79]
	v_max3_f32 v220, v220, v94, v95
	v_mov_b32_e32 v221, v220
	s_nop 1
	v_permlane32_swap_b32_e32 v220, v221
	v_max_f32_e32 v221, v221, v221
	v_max_f32_e32 v220, v220, v220
	v_max_f32_e32 v220, v220, v221
	s_cmp_eq_u32 s26, 0
	s_cbranch_scc1 .Lcf_rare_a
	v_cmp_lt_f32_e32 vcc, 0, v220
	s_cbranch_vccz .LBB0_1255
.Lcf_rare_a:
	v_add_f32_e32 v221, v218, v220
	v_add_f32_e32 v221, 0x40800000, v221
	v_and_b32_e32 v222, 0xffff0000, v221
	v_cmp_lt_f32_e32 vcc, v222, v221
	v_add_u32_e32 v223, 0x10000, v222
	s_nop 0
	v_cndmask_b32_e32 v222, v222, v223, vcc
	v_max_f32_e32 v223, v218, v222
	s_cmp_eq_u32 s26, 0
	s_cselect_b64 vcc, -1, 0
	s_nop 1
	v_cndmask_b32_e32 v222, v223, v222, vcc
	v_sub_f32_e32 v223, v218, v222
	v_exp_f32_e32 v224, v223
	v_add_f32_e32 v112, v223, v112
	v_add_f32_e32 v113, v223, v113
	v_add_f32_e32 v114, v223, v114
	v_add_f32_e32 v115, v223, v115
	v_add_f32_e32 v116, v223, v116
	v_add_f32_e32 v117, v223, v117
	v_add_f32_e32 v118, v223, v118
	v_add_f32_e32 v119, v223, v119
	v_add_f32_e32 v120, v223, v120
	v_add_f32_e32 v121, v223, v121
	v_add_f32_e32 v122, v223, v122
	v_add_f32_e32 v123, v223, v123
	v_add_f32_e32 v124, v223, v124
	v_add_f32_e32 v125, v223, v125
	v_add_f32_e32 v126, v223, v126
	v_add_f32_e32 v127, v223, v127
	v_add_f32_e32 v80, v223, v80
	v_add_f32_e32 v81, v223, v81
	v_add_f32_e32 v82, v223, v82
	v_add_f32_e32 v83, v223, v83
	v_add_f32_e32 v84, v223, v84
	v_add_f32_e32 v85, v223, v85
	v_add_f32_e32 v86, v223, v86
	v_add_f32_e32 v87, v223, v87
	v_add_f32_e32 v88, v223, v88
	v_add_f32_e32 v89, v223, v89
	v_add_f32_e32 v90, v223, v90
	v_add_f32_e32 v91, v223, v91
	v_add_f32_e32 v92, v223, v92
	v_add_f32_e32 v93, v223, v93
	v_add_f32_e32 v94, v223, v94
	v_add_f32_e32 v95, v223, v95
	v_mov_b32_e32 v218, v222
	v_xor_b32_e32 v223, 0x80000000, v222
	v_cmp_ne_u32_e32 vcc, 0, v244
	v_lshrrev_b32_e32 v223, 16, v223
	s_nop 1
	v_cndmask_b32_e32 v248, 0, v223, vcc
	s_cmp_eq_u32 s26, 0
	s_cbranch_scc1 .LBB0_1255
	v_pk_mul_f32 v[62:63], v[62:63], v[224:225] op_sel_hi:[1,0]
	v_pk_mul_f32 v[60:61], v[60:61], v[224:225] op_sel_hi:[1,0]
	v_pk_mul_f32 v[58:59], v[58:59], v[224:225] op_sel_hi:[1,0]
	v_pk_mul_f32 v[56:57], v[56:57], v[224:225] op_sel_hi:[1,0]
	v_pk_mul_f32 v[54:55], v[54:55], v[224:225] op_sel_hi:[1,0]
	v_pk_mul_f32 v[52:53], v[52:53], v[224:225] op_sel_hi:[1,0]
	v_pk_mul_f32 v[50:51], v[50:51], v[224:225] op_sel_hi:[1,0]
	v_pk_mul_f32 v[48:49], v[48:49], v[224:225] op_sel_hi:[1,0]
	v_pk_mul_f32 v[46:47], v[46:47], v[224:225] op_sel_hi:[1,0]
	v_pk_mul_f32 v[44:45], v[44:45], v[224:225] op_sel_hi:[1,0]
	v_pk_mul_f32 v[42:43], v[42:43], v[224:225] op_sel_hi:[1,0]
	v_pk_mul_f32 v[40:41], v[40:41], v[224:225] op_sel_hi:[1,0]
	v_pk_mul_f32 v[38:39], v[38:39], v[224:225] op_sel_hi:[1,0]
	v_pk_mul_f32 v[36:37], v[36:37], v[224:225] op_sel_hi:[1,0]
	v_pk_mul_f32 v[34:35], v[34:35], v[224:225] op_sel_hi:[1,0]
	v_pk_mul_f32 v[32:33], v[32:33], v[224:225] op_sel_hi:[1,0]
	v_mul_f32_e32 v212, v212, v224
; DI void attn_item(const Params& P, int item, unsigned char* lds) {
;     ...
;     SOFTMAX(s10, s11, m1, l1, O10, O11);
.LBB0_1255:
	v_max_f32_e32 v220, v97, v97
	v_max_f32_e32 v221, v96, v96
	v_max_f32_e32 v220, v221, v220
	v_max3_f32 v220, v220, v98, v99
	v_max3_f32 v220, v220, v100, v101
	v_max3_f32 v220, v220, v102, v103
	v_max3_f32 v220, v220, v104, v105
	v_max3_f32 v220, v220, v106, v107
	v_max3_f32 v220, v220, v108, v109
	v_max3_f32 v220, v220, v110, v111
	v_max3_f32 v220, v220, v64, v65
	v_max3_f32 v220, v220, v66, v67
	v_max3_f32 v220, v220, v68, v69
	v_max3_f32 v220, v220, v70, v71
	v_max3_f32 v220, v220, v72, v73
	v_max3_f32 v220, v220, v74, v75
	v_max3_f32 v220, v220, v76, v77
	v_max3_f32 v220, v220, v78, v79
	v_mov_b32_e32 v221, v220
	s_nop 1
	v_permlane32_swap_b32_e32 v220, v221
	v_max_f32_e32 v221, v221, v221
	v_max_f32_e32 v220, v220, v220
	v_max_f32_e32 v220, v220, v221
	s_cmp_eq_u32 s26, 0
	s_cbranch_scc1 .Lcf_rare_b
	v_cmp_lt_f32_e32 vcc, 0, v220
	s_cbranch_vccz .LBB0_1257
.Lcf_rare_b:
	v_add_f32_e32 v221, v217, v220
	v_add_f32_e32 v221, 0x40800000, v221
	v_and_b32_e32 v222, 0xffff0000, v221
	v_cmp_lt_f32_e32 vcc, v222, v221
	v_add_u32_e32 v223, 0x10000, v222
	s_nop 0
	v_cndmask_b32_e32 v222, v222, v223, vcc
	v_max_f32_e32 v223, v217, v222
	s_cmp_eq_u32 s26, 0
	s_cselect_b64 vcc, -1, 0
	s_nop 1
	v_cndmask_b32_e32 v222, v223, v222, vcc
	v_sub_f32_e32 v223, v217, v222
	v_exp_f32_e32 v224, v223
	v_add_f32_e32 v96, v223, v96
	v_add_f32_e32 v97, v223, v97
	v_add_f32_e32 v98, v223, v98
	v_add_f32_e32 v99, v223, v99
	v_add_f32_e32 v100, v223, v100
	v_add_f32_e32 v101, v223, v101
	v_add_f32_e32 v102, v223, v102
	v_add_f32_e32 v103, v223, v103
	v_add_f32_e32 v104, v223, v104
	v_add_f32_e32 v105, v223, v105
	v_add_f32_e32 v106, v223, v106
	v_add_f32_e32 v107, v223, v107
	v_add_f32_e32 v108, v223, v108
	v_add_f32_e32 v109, v223, v109
	v_add_f32_e32 v110, v223, v110
	v_add_f32_e32 v111, v223, v111
	v_add_f32_e32 v64, v223, v64
	v_add_f32_e32 v65, v223, v65
	v_add_f32_e32 v66, v223, v66
	v_add_f32_e32 v67, v223, v67
	v_add_f32_e32 v68, v223, v68
	v_add_f32_e32 v69, v223, v69
	v_add_f32_e32 v70, v223, v70
	v_add_f32_e32 v71, v223, v71
	v_add_f32_e32 v72, v223, v72
	v_add_f32_e32 v73, v223, v73
	v_add_f32_e32 v74, v223, v74
	v_add_f32_e32 v75, v223, v75
	v_add_f32_e32 v76, v223, v76
	v_add_f32_e32 v77, v223, v77
	v_add_f32_e32 v78, v223, v78
	v_add_f32_e32 v79, v223, v79
	v_mov_b32_e32 v217, v222
	v_xor_b32_e32 v223, 0x80000000, v222
	v_cmp_ne_u32_e32 vcc, 0, v244
	v_lshrrev_b32_e32 v223, 16, v223
	s_nop 1
	v_cndmask_b32_e32 v252, 0, v223, vcc
	s_cmp_eq_u32 s26, 0
	s_cbranch_scc1 .LBB0_1257
	v_pk_mul_f32 v[30:31], v[30:31], v[224:225] op_sel_hi:[1,0]
	v_pk_mul_f32 v[28:29], v[28:29], v[224:225] op_sel_hi:[1,0]
	v_pk_mul_f32 v[26:27], v[26:27], v[224:225] op_sel_hi:[1,0]
	v_pk_mul_f32 v[24:25], v[24:25], v[224:225] op_sel_hi:[1,0]
	v_pk_mul_f32 v[22:23], v[22:23], v[224:225] op_sel_hi:[1,0]
	v_pk_mul_f32 v[20:21], v[20:21], v[224:225] op_sel_hi:[1,0]
	v_pk_mul_f32 v[18:19], v[18:19], v[224:225] op_sel_hi:[1,0]
	v_pk_mul_f32 v[16:17], v[16:17], v[224:225] op_sel_hi:[1,0]
	v_pk_mul_f32 v[14:15], v[14:15], v[224:225] op_sel_hi:[1,0]
	v_pk_mul_f32 v[12:13], v[12:13], v[224:225] op_sel_hi:[1,0]
	v_pk_mul_f32 v[10:11], v[10:11], v[224:225] op_sel_hi:[1,0]
	v_pk_mul_f32 v[8:9], v[8:9], v[224:225] op_sel_hi:[1,0]
	v_pk_mul_f32 v[6:7], v[6:7], v[224:225] op_sel_hi:[1,0]
	v_pk_mul_f32 v[4:5], v[4:5], v[224:225] op_sel_hi:[1,0]
	v_pk_mul_f32 v[2:3], v[2:3], v[224:225] op_sel_hi:[1,0]
	v_pk_mul_f32 v[0:1], v[0:1], v[224:225] op_sel_hi:[1,0]
	v_mul_f32_e32 v193, v193, v224
; #define TLOAD(kt) do { const int key0 = (kt) * 64; \
;     rk = *(const uint4*)(KN + (size_t)(key0 + (tid >> 3)) * 64 + (tid & 7) * 8); \
;     if (tid < 256) rr = *(const uint4*)(KR + (size_t)(key0 + (tid >> 2)) * 32 + (tid & 3) * 8); \
;     rv = *(const uint4*)(VT + (size_t)(tid >> 3) * LK + key0 + (tid & 7) * 8); } while (0)
; #define TSTORE(st) do { bf16_t* Ks = Kl + (st) * KB; \
;     *(uint4*)(Ks + (tid >> 3) * AK_LD + (tid & 7) * 8) = rk; \
;     if (tid < 256) *(uint4*)(Ks + (tid >> 2) * AK_LD + 64 + (tid & 3) * 8) = rr; \
;     *(uint4*)(Vl + (st) * VB + (tid >> 3) * AV_LD + (tid & 7) * 8) = rv; } while (0)
; #define QKSTEP(off, qa, qbb) do { const bf16x8 a0 = *(const bf16x8*)(kp + (off)), a1 = *(const bf16x8*)(kp + 32 * AK_LD + (off)); \
;       s00 = MF(a0, qa, s00); s01 = MF(a1, qa, s01); s10 = MF(a0, qbb, s10); s11 = MF(a1, qbb, s11); } while (0)
; #define PVSTEP(sx, sy, o, koff) do { union { uint4 u; bf16x8 v; } p0, p1; p0.u = PK8(sx, o); p1.u = PK8(sy, o); \
;       const bf16x8 v0 = *(const bf16x8*)(vp + (koff)), v1 = *(const bf16x8*)(vp + 32 * AV_LD + (koff)); \
;       O00 = MF(v0, p0.v, O00); O01 = MF(v1, p0.v, O01); O10 = MF(v0, p1.v, O10); O11 = MF(v1, p1.v, O11); } while (0)
; DI void attn_item(const Params& P, int item, unsigned char* lds) {
;     ...
;   const int NKT = LK / 64;
;   __syncthreads();
;   TLOAD(0); TSTORE(0);
;   __syncthreads();
;   for (int kt = 0; kt < NKT; ++kt) {
;     { const int k1 = (kt + 1 < NKT) ? kt + 1 : NKT - 1; TLOAD(k1); }
;     const bf16_t* Ks = Kl + (kt & 1) * KB; const bf16_t* Vs = Vl + (kt & 1) * VB;
;     f32x16 s00, s01, s10, s11;
; #pragma unroll
;     for (int e = 0; e < 16; ++e) { s00[e] = 0.f; s01[e] = 0.f; s10[e] = 0.f; s11[e] = 0.f; }
;     const bf16_t* kp = Ks + l31 * AK_LD + hh * 8;
;     ...
;     QKSTEP(0, qa0, qb0); QKSTEP(16, qa1, qb1); QKSTEP(32, qa2, qb2); QKSTEP(48, qa3, qb3); QKSTEP(64, qa4, qb4); QKSTEP(80, qa5, qb5);
;     ...
;     SOFTMAX(s00, s01, m0, l0, O00, O01);
;     SOFTMAX(s10, s11, m1, l1, O10, O11);
;     const bf16_t* vp = Vs + l31 * AV_LD + 8 * hh;
;     ...
;     PVSTEP(s00, s10, 0, 0); PVSTEP(s00, s10, 8, 16); PVSTEP(s01, s11, 0, 32); PVSTEP(s01, s11, 8, 48);
;     ...
;     TSTORE((kt + 1) & 1);
.LBB0_1257:
	s_mulk_i32 s24, 0x2400
	v_add_u32_e32 v242, s24, v216
	ds_read_b128 v[222:225], v242 offset:26624
	ds_read_b128 v[230:233], v242 offset:31232
	ds_read_b128 v[234:237], v242 offset:26656
	ds_read_b128 v[238:241], v242 offset:31264
	v_exp_f32_e32 v112, v112
	v_exp_f32_e32 v113, v113
	v_exp_f32_e32 v114, v114
	v_exp_f32_e32 v115, v115
	v_exp_f32_e32 v116, v116
	v_exp_f32_e32 v117, v117
	v_exp_f32_e32 v118, v118
	v_exp_f32_e32 v119, v119
	v_cvt_pk_bf16_f32 v226, v112, v113
	v_cvt_pk_bf16_f32 v227, v114, v115
	v_cvt_pk_bf16_f32 v228, v116, v117
	v_cvt_pk_bf16_f32 v229, v118, v119
	v_exp_f32_e32 v96, v96
	v_exp_f32_e32 v97, v97
	v_exp_f32_e32 v98, v98
	v_exp_f32_e32 v99, v99
	v_exp_f32_e32 v100, v100
	v_exp_f32_e32 v101, v101
	v_exp_f32_e32 v102, v102
	v_exp_f32_e32 v103, v103
	s_waitcnt lgkmcnt(2)
	v_mfma_f32_32x32x16_bf16 v[48:63], v[222:225], v[226:229], v[48:63]
	v_mfma_f32_32x32x16_bf16 v[32:47], v[230:233], v[226:229], v[32:47]
	v_cvt_pk_bf16_f32 v226, v96, v97
	v_cvt_pk_bf16_f32 v227, v98, v99
	v_cvt_pk_bf16_f32 v228, v100, v101
	v_cvt_pk_bf16_f32 v229, v102, v103
	v_exp_f32_e32 v120, v120
	v_exp_f32_e32 v121, v121
	v_exp_f32_e32 v122, v122
	v_exp_f32_e32 v123, v123
	v_exp_f32_e32 v124, v124
	v_exp_f32_e32 v125, v125
	v_exp_f32_e32 v126, v126
	v_exp_f32_e32 v127, v127
	v_pk_add_f32 v[112:113], v[112:113], v[114:115]
	v_pk_add_f32 v[116:117], v[116:117], v[118:119]
	v_pk_add_f32 v[112:113], v[112:113], v[116:117]
	v_mfma_f32_32x32x16_bf16 v[16:31], v[222:225], v[226:229], v[16:31]
	v_mfma_f32_32x32x16_bf16 v[0:15], v[230:233], v[226:229], v[0:15]
	ds_read_b128 v[222:225], v242 offset:26688
	ds_read_b128 v[230:233], v242 offset:31296
	v_cvt_pk_bf16_f32 v226, v120, v121
	v_cvt_pk_bf16_f32 v227, v122, v123
	v_cvt_pk_bf16_f32 v228, v124, v125
	v_cvt_pk_bf16_f32 v229, v126, v127
	v_exp_f32_e32 v104, v104
	v_exp_f32_e32 v105, v105
	v_exp_f32_e32 v106, v106
	v_exp_f32_e32 v107, v107
	v_exp_f32_e32 v108, v108
	v_exp_f32_e32 v109, v109
	v_exp_f32_e32 v110, v110
	v_exp_f32_e32 v111, v111
	v_pk_add_f32 v[96:97], v[96:97], v[98:99]
	v_pk_add_f32 v[100:101], v[100:101], v[102:103]
	v_pk_add_f32 v[96:97], v[96:97], v[100:101]
	s_waitcnt lgkmcnt(2)
	v_mfma_f32_32x32x16_bf16 v[48:63], v[234:237], v[226:229], v[48:63]
	v_mfma_f32_32x32x16_bf16 v[32:47], v[238:241], v[226:229], v[32:47]
	v_cvt_pk_bf16_f32 v226, v104, v105
	v_cvt_pk_bf16_f32 v227, v106, v107
	v_cvt_pk_bf16_f32 v228, v108, v109
	v_cvt_pk_bf16_f32 v229, v110, v111
	v_exp_f32_e32 v80, v80
	v_exp_f32_e32 v81, v81
	v_exp_f32_e32 v82, v82
	v_exp_f32_e32 v83, v83
	v_exp_f32_e32 v84, v84
	v_exp_f32_e32 v85, v85
	v_exp_f32_e32 v86, v86
	v_exp_f32_e32 v87, v87
	v_pk_add_f32 v[120:121], v[120:121], v[122:123]
	v_pk_add_f32 v[124:125], v[124:125], v[126:127]
	v_pk_add_f32 v[120:121], v[120:121], v[124:125]
	v_mfma_f32_32x32x16_bf16 v[16:31], v[234:237], v[226:229], v[16:31]
	v_mfma_f32_32x32x16_bf16 v[0:15], v[238:241], v[226:229], v[0:15]
	ds_read_b128 v[234:237], v242 offset:26720
	ds_read_b128 v[238:241], v242 offset:31328
	v_cvt_pk_bf16_f32 v226, v80, v81
	v_cvt_pk_bf16_f32 v227, v82, v83
	v_cvt_pk_bf16_f32 v228, v84, v85
	v_cvt_pk_bf16_f32 v229, v86, v87
	v_exp_f32_e32 v64, v64
	v_exp_f32_e32 v65, v65
	v_exp_f32_e32 v66, v66
	v_exp_f32_e32 v67, v67
	v_exp_f32_e32 v68, v68
	v_exp_f32_e32 v69, v69
	v_exp_f32_e32 v70, v70
	v_exp_f32_e32 v71, v71
	v_pk_add_f32 v[104:105], v[104:105], v[106:107]
	v_pk_add_f32 v[108:109], v[108:109], v[110:111]
	v_pk_add_f32 v[104:105], v[104:105], v[108:109]
	s_waitcnt lgkmcnt(2)
	v_mfma_f32_32x32x16_bf16 v[48:63], v[222:225], v[226:229], v[48:63]
	v_mfma_f32_32x32x16_bf16 v[32:47], v[230:233], v[226:229], v[32:47]
	v_cvt_pk_bf16_f32 v226, v64, v65
	v_cvt_pk_bf16_f32 v227, v66, v67
	v_cvt_pk_bf16_f32 v228, v68, v69
	v_cvt_pk_bf16_f32 v229, v70, v71
	v_exp_f32_e32 v88, v88
	v_exp_f32_e32 v89, v89
	v_exp_f32_e32 v90, v90
	v_exp_f32_e32 v91, v91
	v_exp_f32_e32 v92, v92
	v_exp_f32_e32 v93, v93
	v_exp_f32_e32 v94, v94
	v_exp_f32_e32 v95, v95
	v_pk_add_f32 v[80:81], v[80:81], v[82:83]
	v_pk_add_f32 v[84:85], v[84:85], v[86:87]
	v_pk_add_f32 v[80:81], v[80:81], v[84:85]
	v_mfma_f32_32x32x16_bf16 v[16:31], v[222:225], v[226:229], v[16:31]
	v_mfma_f32_32x32x16_bf16 v[0:15], v[230:233], v[226:229], v[0:15]
	v_cvt_pk_bf16_f32 v226, v88, v89
	v_cvt_pk_bf16_f32 v227, v90, v91
	v_cvt_pk_bf16_f32 v228, v92, v93
	v_cvt_pk_bf16_f32 v229, v94, v95
	v_exp_f32_e32 v72, v72
	v_exp_f32_e32 v73, v73
	v_exp_f32_e32 v74, v74
	v_exp_f32_e32 v75, v75
	v_exp_f32_e32 v76, v76
	v_exp_f32_e32 v77, v77
	v_exp_f32_e32 v78, v78
	v_exp_f32_e32 v79, v79
	v_pk_add_f32 v[64:65], v[64:65], v[66:67]
	v_pk_add_f32 v[68:69], v[68:69], v[70:71]
	v_pk_add_f32 v[64:65], v[64:65], v[68:69]
	s_waitcnt lgkmcnt(0)
	v_mfma_f32_32x32x16_bf16 v[48:63], v[234:237], v[226:229], v[48:63]
	v_mfma_f32_32x32x16_bf16 v[32:47], v[238:241], v[226:229], v[32:47]
	v_cvt_pk_bf16_f32 v226, v72, v73
	v_cvt_pk_bf16_f32 v227, v74, v75
	v_cvt_pk_bf16_f32 v228, v76, v77
	v_cvt_pk_bf16_f32 v229, v78, v79
	v_pk_add_f32 v[88:89], v[88:89], v[90:91]
	v_pk_add_f32 v[92:93], v[92:93], v[94:95]
	v_pk_add_f32 v[88:89], v[88:89], v[92:93]
	s_add_i32 s26, s26, 1
	s_and_b32 s27, s26, 1
	s_mul_i32 s44, s27, 0x3400
	v_lshlrev_b32_e32 v220, 1, v195
	v_add3_u32 v220, s44, v220, v188
	v_mfma_f32_32x32x16_bf16 v[16:31], v[234:237], v[226:229], v[16:31]
	v_mfma_f32_32x32x16_bf16 v[0:15], v[238:241], v[226:229], v[0:15]
	s_waitcnt vmcnt(1)
	ds_write_b128 v220, v[180:183]
	s_cmp_eq_u64 s[4:5], 0
	s_cbranch_scc1 .Lcf_nokr
	v_lshlrev_b32_e32 v221, 1, v194
	v_add3_u32 v221, s44, v215, v221
	ds_write_b128 v221, v[128:131] offset:128
.Lcf_nokr:
	v_pk_add_f32 v[72:73], v[72:73], v[74:75]
	v_pk_add_f32 v[76:77], v[76:77], v[78:79]
	v_pk_add_f32 v[72:73], v[72:73], v[76:77]
	v_pk_add_f32 v[112:113], v[112:113], v[120:121]
	v_pk_add_f32 v[80:81], v[80:81], v[88:89]
	v_pk_add_f32 v[96:97], v[96:97], v[104:105]
	v_pk_add_f32 v[64:65], v[64:65], v[72:73]
	v_pk_add_f32 v[112:113], v[112:113], v[80:81]
	v_pk_add_f32 v[96:97], v[96:97], v[64:65]
	v_add_f32_e32 v112, v112, v113
	v_add_f32_e32 v96, v96, v97
	v_add_f32_e32 v212, v212, v112
	v_add_f32_e32 v193, v193, v96
	s_branch .LBB0_1250

; __global__ void __launch_bounds__(NTHR) mega(Params P) {
;   __shared__ __attribute__((aligned(16))) unsigned char lds[LDS_BYTES];
	.amdhsa_kernel _Z4mega6Params
		.amdhsa_group_segment_fixed_size 147728
		.amdhsa_private_segment_fixed_size 0
		.amdhsa_kernarg_size 472
		.amdhsa_user_sgpr_count 2
		.amdhsa_user_sgpr_dispatch_ptr 0
		.amdhsa_user_sgpr_queue_ptr 0
		.amdhsa_user_sgpr_kernarg_segment_ptr 1
		.amdhsa_user_sgpr_dispatch_id 0
		.amdhsa_user_sgpr_kernarg_preload_length 0
		.amdhsa_user_sgpr_kernarg_preload_offset 0
		.amdhsa_user_sgpr_private_segment_size 0
		.amdhsa_uses_dynamic_stack 0
		.amdhsa_enable_private_segment 0
		.amdhsa_system_sgpr_workgroup_id_x 1
		.amdhsa_system_sgpr_workgroup_id_y 0
		.amdhsa_system_sgpr_workgroup_id_z 0
		.amdhsa_system_sgpr_workgroup_info 0
		.amdhsa_system_vgpr_workitem_id 2
		.amdhsa_next_free_vgpr 256
		.amdhsa_next_free_sgpr 98
		.amdhsa_accum_offset 256
		.amdhsa_reserve_vcc 1
		.amdhsa_float_round_mode_32 0
		.amdhsa_float_round_mode_16_64 0
		.amdhsa_float_denorm_mode_32 3
		.amdhsa_float_denorm_mode_16_64 3
		.amdhsa_dx10_clamp 1
		.amdhsa_ieee_mode 1
		.amdhsa_fp16_overflow 0
		.amdhsa_tg_split 0
		.amdhsa_exception_fp_ieee_invalid_op 0
		.amdhsa_exception_fp_denorm_src 0
		.amdhsa_exception_fp_ieee_div_zero 0
		.amdhsa_exception_fp_ieee_overflow 0
		.amdhsa_exception_fp_ieee_underflow 0
		.amdhsa_exception_fp_ieee_inexact 0
		.amdhsa_exception_int_div_zero 0
	.end_amdhsa_kernel

; __global__ void __launch_bounds__(NTHR) mega(Params P) {
;   __shared__ __attribute__((aligned(16))) unsigned char lds[LDS_BYTES];
amdhsa.kernels:
  - .agpr_count:     0
    .args:
      - .offset:         0
        .size:           216
        .value_kind:     by_value
      - .offset:         216
        .size:           4
        .value_kind:     hidden_block_count_x
      - .offset:         220
        .size:           4
        .value_kind:     hidden_block_count_y
      - .offset:         224
        .size:           4
        .value_kind:     hidden_block_count_z
      - .offset:         228
        .size:           2
        .value_kind:     hidden_group_size_x
      - .offset:         230
        .size:           2
        .value_kind:     hidden_group_size_y
      - .offset:         232
        .size:           2
        .value_kind:     hidden_group_size_z
      - .offset:         234
        .size:           2
        .value_kind:     hidden_remainder_x
      - .offset:         236
        .size:           2
        .value_kind:     hidden_remainder_y
      - .offset:         238
        .size:           2
        .value_kind:     hidden_remainder_z
      - .offset:         256
        .size:           8
        .value_kind:     hidden_global_offset_x
      - .offset:         264
        .size:           8
        .value_kind:     hidden_global_offset_y
      - .offset:         272
        .size:           8
        .value_kind:     hidden_global_offset_z
      - .offset:         280
        .size:           2
        .value_kind:     hidden_grid_dims
      - .offset:         304
        .size:           8
        .value_kind:     hidden_multigrid_sync_arg
    .group_segment_fixed_size: 147728
    .kernarg_segment_align: 8
    .kernarg_segment_size: 472
    .language:       OpenCL C
    .language_version:
      - 2
      - 0
    .max_flat_workgroup_size: 512
    .name:           _Z4mega6Params
    .private_segment_fixed_size: 0
    .sgpr_count:     104
    .sgpr_spill_count: 38
    .symbol:         _Z4mega6Params.kd
    .uniform_work_group_size: 1
    .uses_dynamic_stack: false
    .vgpr_count:     256
    .vgpr_spill_count: 0
    .wavefront_size: 64
